# conv: contiguous filter layout, window rows loaded as 4 dwords instead of 8 ushort with per-lane index math
# speedup vs baseline: 1.0397x; 1.0397x over previous
; __device__ __forceinline__ unsigned pk2(float lo, float hi) { const f32x2_t f = {lo, hi}; const bf16x2_t b = __builtin_convertvector(f, bf16x2_t); return __builtin_bit_cast(unsigned, b); }
;   __device__ __forceinline__ void operator()(const f32x4 (&acc)[2][2][4][2], const pg8::Unit& u, int wr, int wc, int fr, int fq) const {
;     ...
;         const int pr = col0 + bj * 128; const int L = pr < 2048 ? 2048 : 16384; const int p0 = pr < 2048 ? pr : pr - 2048;
;         u16* G = (u16*)(ws + (L == 2048 ? O_G2K : O_G16K));
;         const float tinv = 1.0f / (float)(L - 1);
; #pragma unroll
;         for (int ai = 0; ai < 2; ++ai)
; #pragma unroll
;           for (int m = 0; m < 4; ++m) {
;             const int fc = row0 + ai * 128 + m * 16; const int order = fc >> 11, dir = (fc >> 10) & 1, c = fc & 1023;
;             const float dl = dmin + (dmax - dmin) * ((float)c * (1.0f / 1023.0f));
;             float v[8]; float dk = __expf(-(float)p0 * tinv * dl); const float dstep = __expf(-tinv * dl);
; #pragma unroll
;             for (int e = 0; e < 8; ++e) { v[e] = acc[ai][bj][m][e >> 2][e & 3] * dk; dk *= dstep; }
;             u16* base = G + (size_t)(order * 1024 + c) * (size_t)(2 * L);
;             u32x4 o;
;             if (dir == 0) { o.x = pk2(v[7], v[6]); o.y = pk2(v[5], v[4]); o.z = pk2(v[3], v[2]); o.w = pk2(v[1], v[0]); *(u32x4*)(base + (L - 8 - p0)) = o; }
;             else { o.x = pk2(v[0], v[1]); o.y = pk2(v[2], v[3]); o.z = pk2(v[4], v[5]); o.w = pk2(v[6], v[7]); *(u32x4*)(base + (L + p0)) = o; }
.LBB0_285:
	s_andn2_b64 vcc, exec, s[10:11]
	s_cbranch_vccnz .LBB0_50
	v_cmp_gt_i32_e64 s[0:1], s94, v174
	v_and_b32_e32 v143, 0x3cf, v176
	s_bitcmp1_b32 s71, 10
	s_waitcnt lgkmcnt(0)
	v_cndmask_b32_e64 v80, v226, v227, s[0:1]
	v_add_u32_e32 v130, -1, v80
	v_cvt_f32_u32_e32 v131, v130
	v_add_u32_e32 v130, 0xfffff800, v174
	v_cndmask_b32_e64 v130, v130, v174, s[0:1]
	s_mov_b64 s[12:13], -1
	v_div_scale_f32 v132, s[10:11], v131, v131, 1.0
	v_rcp_f32_e32 v133, v132
	v_div_scale_f32 v134, vcc, 1.0, v131, 1.0
	s_cselect_b64 s[10:11], -1, 0
	v_fma_f32 v135, -v132, v133, 1.0
	v_fmac_f32_e32 v133, v135, v133
	v_mul_f32_e32 v135, v134, v133
	v_fma_f32 v136, -v132, v135, v134
	v_fmac_f32_e32 v135, v136, v133
	v_cvt_f32_u32_e32 v136, v143
	v_fma_f32 v132, -v132, v135, v134
	v_cvt_f32_i32_e32 v134, v130
	v_div_fmas_f32 v132, v132, v133, v135
	v_div_fixup_f32 v141, v132, v131, 1.0
	v_cmp_eq_u32_e32 vcc, 0, v130
	v_lshlrev_b32_e32 v150, 1, v80
	v_mov_b32_e32 v149, 0
	s_and_b64 vcc, vcc, s[10:11]
	v_cndmask_b32_e32 v148, 0, v150, vcc
	v_mul_f32_e32 v131, 0x3a802008, v136
	v_mul_f32_e64 v142, v141, -v134
	v_fmamk_f32 v140, v131, 0x41447cbd, v219
	v_mul_f32_e32 v131, v140, v142
	v_mul_f32_e32 v131, 0x3fb8aa3b, v131
	v_exp_f32_e32 v132, v131
	v_mul_f32_e64 v131, v140, -v141
	v_mul_f32_e32 v131, 0x3fb8aa3b, v131
	v_exp_f32_e32 v131, v131
	s_and_b64 vcc, exec, s[10:11]
	v_mul_f32_e32 v133, v131, v132
	v_mul_f32_e32 v134, v131, v133
	v_mul_f32_e32 v135, v131, v134
	v_pk_mul_f32 v[126:127], v[132:133], v[126:127]
	v_pk_mul_f32 v[132:133], v[134:135], v[128:129]
	v_mul_f32_e32 v128, v131, v135
	v_mul_f32_e32 v129, v131, v128
	v_pk_mul_f32 v[136:137], v[128:129], v[122:123]
	v_mul_f32_e32 v122, v131, v129
	v_mul_f32_e32 v123, v131, v122
	v_pk_mul_f32 v[134:135], v[122:123], v[124:125]
	s_cbranch_vccz .LBB0_288
	v_cvt_pk_bf16_f32 v122, v126, v127
	v_cvt_pk_bf16_f32 v123, v132, v133
	v_cvt_pk_bf16_f32 v124, v136, v137
	s_mov_b64 s[12:13], 0
.LBB0_288:
	v_add_u32_e32 v128, v80, v130
	v_add_u32_e32 v128, -1, v128
	v_sub_u32_e32 v80, v80, v130
	v_ashrrev_i32_e32 v129, 31, v128
	v_add_u32_e32 v130, -8, v80
	v_ashrrev_i32_e32 v131, 31, v130
	s_andn2_b64 vcc, exec, s[12:13]
	v_mov_b64_e32 v[138:139], v[128:129]
	s_cbranch_vccnz .LBB0_290
	v_pk_mov_b32 v[122:123], v[134:135], v[134:135] op_sel:[1,0]
	v_pk_mov_b32 v[124:125], v[136:137], v[136:137] op_sel:[1,0]
	v_cvt_pk_bf16_f32 v122, v122, v123
	v_cvt_pk_bf16_f32 v123, v124, v125
	v_pk_mov_b32 v[124:125], v[132:133], v[132:133] op_sel:[1,0]
	v_mov_b64_e32 v[138:139], v[130:131]
	v_cvt_pk_bf16_f32 v124, v124, v125
	v_mov_b32_e32 v134, v127
	v_mov_b32_e32 v135, v126
.LBB0_290:
	v_cndmask_b32_e64 v80, v228, v229, s[0:1]
	v_lshl_add_u64 v[132:133], s[88:89], 0, v[80:81]
	v_cndmask_b32_e64 v80, 15, 12, s[0:1]
	s_ashr_i32 s0, s71, 1
	s_and_b32 s71, s0, 0xfffffc00
	v_or_b32_e32 v126, s71, v143
	v_ashrrev_i32_e32 v127, 31, v126
	v_lshlrev_b64 v[136:137], v80, v[126:127]
	v_lshl_add_u64 v[136:137], v[136:137], 1, v[132:133]
	v_cvt_pk_bf16_f32 v125, v134, v135
	v_lshl_add_u64 v[134:135], v[138:139], 1, v[136:137]
	v_or_b32_e32 v137, 16, v143
	v_lshl_add_u64 v[146:147], v[148:149], 0, v[134:135]
	flat_store_dwordx2 v[134:135], v[124:125] offset:8
	flat_store_dword v[134:135], v123 offset:4
	flat_store_short_d16_hi v[134:135], v122 offset:2
	flat_store_short v[146:147], v122
	s_mov_b64 s[0:1], -1
	s_andn2_b64 vcc, exec, s[10:11]
	v_cvt_f32_u32_e32 v122, v137
	v_mul_f32_e32 v122, 0x3a802008, v122
	v_fmamk_f32 v136, v122, 0x41447cbd, v219
	v_mul_f32_e32 v122, v142, v136
	v_mul_f32_e64 v123, v136, -v141
	v_mul_f32_e32 v122, 0x3fb8aa3b, v122
	v_mul_f32_e32 v123, 0x3fb8aa3b, v123
	v_exp_f32_e32 v122, v122
	v_exp_f32_e32 v134, v123
	s_nop 0
	v_mul_f32_e32 v123, v134, v122
	v_pk_mul_f32 v[118:119], v[122:123], v[118:119]
	v_mul_f32_e32 v122, v134, v123
	v_mul_f32_e32 v123, v134, v122
	v_pk_mul_f32 v[120:121], v[122:123], v[120:121]
	v_mul_f32_e32 v122, v134, v123
	v_mul_f32_e32 v123, v134, v122
	v_pk_mul_f32 v[124:125], v[122:123], v[114:115]
	v_mul_f32_e32 v114, v134, v123
	v_mul_f32_e32 v115, v134, v114
	v_pk_mul_f32 v[122:123], v[114:115], v[116:117]
	v_cndmask_b32_e64 v114, 0, 1, s[10:11]
	v_cmp_ne_u32_e64 s[12:13], 1, v114
	s_cbranch_vccnz .LBB0_292
	v_cvt_pk_bf16_f32 v114, v118, v119
	v_cvt_pk_bf16_f32 v115, v120, v121
	v_cvt_pk_bf16_f32 v116, v124, v125
	s_mov_b64 s[0:1], 0

; __device__ __forceinline__ unsigned pk2(float lo, float hi) { const f32x2_t f = {lo, hi}; const bf16x2_t b = __builtin_convertvector(f, bf16x2_t); return __builtin_bit_cast(unsigned, b); }
;   __device__ __forceinline__ void operator()(const f32x4 (&acc)[2][2][4][2], const pg8::Unit& u, int wr, int wc, int fr, int fq) const {
;     ...
;           for (int m = 0; m < 4; ++m) {
;             const int fc = row0 + ai * 128 + m * 16; const int order = fc >> 11, dir = (fc >> 10) & 1, c = fc & 1023;
;             const float dl = dmin + (dmax - dmin) * ((float)c * (1.0f / 1023.0f));
;             float v[8]; float dk = __expf(-(float)p0 * tinv * dl); const float dstep = __expf(-tinv * dl);
; #pragma unroll
;             for (int e = 0; e < 8; ++e) { v[e] = acc[ai][bj][m][e >> 2][e & 3] * dk; dk *= dstep; }
;             u16* base = G + (size_t)(order * 1024 + c) * (size_t)(2 * L);
;             u32x4 o;
;             if (dir == 0) { o.x = pk2(v[7], v[6]); o.y = pk2(v[5], v[4]); o.z = pk2(v[3], v[2]); o.w = pk2(v[1], v[0]); *(u32x4*)(base + (L - 8 - p0)) = o; }
;             else { o.x = pk2(v[0], v[1]); o.y = pk2(v[2], v[3]); o.z = pk2(v[4], v[5]); o.w = pk2(v[6], v[7]); *(u32x4*)(base + (L + p0)) = o; }
.LBB0_294:
	v_or_b32_e32 v118, s71, v137
	v_ashrrev_i32_e32 v119, 31, v118
	v_lshlrev_b64 v[120:121], v80, v[118:119]
	v_lshl_add_u64 v[120:121], v[120:121], 1, v[132:133]
	v_cvt_pk_bf16_f32 v117, v122, v123
	v_lshl_add_u64 v[120:121], v[134:135], 1, v[120:121]
	v_or_b32_e32 v123, 32, v143
	v_lshl_add_u64 v[146:147], v[148:149], 0, v[120:121]
	flat_store_dwordx2 v[120:121], v[116:117] offset:8
	flat_store_dword v[120:121], v115 offset:4
	flat_store_short_d16_hi v[120:121], v114 offset:2
	flat_store_short v[146:147], v114
	s_mov_b64 s[0:1], -1
	s_and_b64 vcc, exec, s[12:13]
	v_cvt_f32_u32_e32 v114, v123
	v_mul_f32_e32 v114, 0x3a802008, v114
	v_fmamk_f32 v122, v114, 0x41447cbd, v219
	v_mul_f32_e32 v114, v142, v122
	v_mul_f32_e64 v115, v122, -v141
	v_mul_f32_e32 v114, 0x3fb8aa3b, v114
	v_mul_f32_e32 v115, 0x3fb8aa3b, v115
	v_exp_f32_e32 v114, v114
	v_exp_f32_e32 v120, v115
	s_nop 0
	v_mul_f32_e32 v115, v120, v114
	v_pk_mul_f32 v[110:111], v[114:115], v[110:111]
	v_mul_f32_e32 v114, v120, v115
	v_mul_f32_e32 v115, v120, v114
	v_pk_mul_f32 v[112:113], v[114:115], v[112:113]
	v_mul_f32_e32 v114, v120, v115
	v_mul_f32_e32 v115, v120, v114
	v_pk_mul_f32 v[116:117], v[114:115], v[106:107]
	v_mul_f32_e32 v106, v120, v115
	v_mul_f32_e32 v107, v120, v106
	v_pk_mul_f32 v[114:115], v[106:107], v[108:109]
	s_cbranch_vccnz .LBB0_296
	v_cvt_pk_bf16_f32 v106, v110, v111
	v_cvt_pk_bf16_f32 v107, v112, v113
	v_cvt_pk_bf16_f32 v108, v116, v117
	s_mov_b64 s[0:1], 0

; __device__ __forceinline__ unsigned pk2(float lo, float hi) { const f32x2_t f = {lo, hi}; const bf16x2_t b = __builtin_convertvector(f, bf16x2_t); return __builtin_bit_cast(unsigned, b); }
;   __device__ __forceinline__ void operator()(const f32x4 (&acc)[2][2][4][2], const pg8::Unit& u, int wr, int wc, int fr, int fq) const {
;     ...
;           for (int m = 0; m < 4; ++m) {
;             const int fc = row0 + ai * 128 + m * 16; const int order = fc >> 11, dir = (fc >> 10) & 1, c = fc & 1023;
;             const float dl = dmin + (dmax - dmin) * ((float)c * (1.0f / 1023.0f));
;             float v[8]; float dk = __expf(-(float)p0 * tinv * dl); const float dstep = __expf(-tinv * dl);
; #pragma unroll
;             for (int e = 0; e < 8; ++e) { v[e] = acc[ai][bj][m][e >> 2][e & 3] * dk; dk *= dstep; }
;             u16* base = G + (size_t)(order * 1024 + c) * (size_t)(2 * L);
;             u32x4 o;
;             if (dir == 0) { o.x = pk2(v[7], v[6]); o.y = pk2(v[5], v[4]); o.z = pk2(v[3], v[2]); o.w = pk2(v[1], v[0]); *(u32x4*)(base + (L - 8 - p0)) = o; }
;             else { o.x = pk2(v[0], v[1]); o.y = pk2(v[2], v[3]); o.z = pk2(v[4], v[5]); o.w = pk2(v[6], v[7]); *(u32x4*)(base + (L + p0)) = o; }
.LBB0_298:
	v_or_b32_e32 v110, s71, v123
	v_ashrrev_i32_e32 v111, 31, v110
	v_lshlrev_b64 v[112:113], v80, v[110:111]
	v_lshl_add_u64 v[112:113], v[112:113], 1, v[132:133]
	v_cvt_pk_bf16_f32 v109, v114, v115
	v_lshl_add_u64 v[112:113], v[120:121], 1, v[112:113]
	v_or_b32_e32 v115, 48, v143
	v_lshl_add_u64 v[146:147], v[148:149], 0, v[112:113]
	flat_store_dwordx2 v[112:113], v[108:109] offset:8
	flat_store_dword v[112:113], v107 offset:4
	flat_store_short_d16_hi v[112:113], v106 offset:2
	flat_store_short v[146:147], v106
	s_mov_b64 s[0:1], -1
	s_and_b64 vcc, exec, s[12:13]
	v_cvt_f32_u32_e32 v106, v115
	v_mul_f32_e32 v106, 0x3a802008, v106
	v_fmamk_f32 v114, v106, 0x41447cbd, v219
	v_mul_f32_e32 v106, v142, v114
	v_mul_f32_e64 v107, v114, -v141
	v_mul_f32_e32 v106, 0x3fb8aa3b, v106
	v_mul_f32_e32 v107, 0x3fb8aa3b, v107
	v_exp_f32_e32 v106, v106
	v_exp_f32_e32 v112, v107
	s_nop 0
	v_mul_f32_e32 v107, v112, v106
	v_mul_f32_e32 v108, v112, v107
	v_mul_f32_e32 v109, v112, v108
	v_pk_mul_f32 v[102:103], v[106:107], v[102:103]
	v_pk_mul_f32 v[106:107], v[108:109], v[104:105]
	v_mul_f32_e32 v104, v112, v109
	v_mul_f32_e32 v105, v112, v104
	v_pk_mul_f32 v[108:109], v[104:105], v[98:99]
	v_mul_f32_e32 v98, v112, v105
	v_mul_f32_e32 v99, v112, v98
	v_pk_mul_f32 v[104:105], v[98:99], v[100:101]
	s_cbranch_vccnz .LBB0_300
	v_cvt_pk_bf16_f32 v98, v102, v103
	v_cvt_pk_bf16_f32 v99, v106, v107
	v_cvt_pk_bf16_f32 v100, v108, v109
	s_mov_b64 s[0:1], 0

; __device__ __forceinline__ unsigned pk2(float lo, float hi) { const f32x2_t f = {lo, hi}; const bf16x2_t b = __builtin_convertvector(f, bf16x2_t); return __builtin_bit_cast(unsigned, b); }
;   __device__ __forceinline__ void operator()(const f32x4 (&acc)[2][2][4][2], const pg8::Unit& u, int wr, int wc, int fr, int fq) const {
;     ...
;         for (int ai = 0; ai < 2; ++ai)
; #pragma unroll
;           for (int m = 0; m < 4; ++m) {
;             const int fc = row0 + ai * 128 + m * 16; const int order = fc >> 11, dir = (fc >> 10) & 1, c = fc & 1023;
;             const float dl = dmin + (dmax - dmin) * ((float)c * (1.0f / 1023.0f));
;             float v[8]; float dk = __expf(-(float)p0 * tinv * dl); const float dstep = __expf(-tinv * dl);
; #pragma unroll
;             for (int e = 0; e < 8; ++e) { v[e] = acc[ai][bj][m][e >> 2][e & 3] * dk; dk *= dstep; }
;             u16* base = G + (size_t)(order * 1024 + c) * (size_t)(2 * L);
;             u32x4 o;
;             if (dir == 0) { o.x = pk2(v[7], v[6]); o.y = pk2(v[5], v[4]); o.z = pk2(v[3], v[2]); o.w = pk2(v[1], v[0]); *(u32x4*)(base + (L - 8 - p0)) = o; }
;             else { o.x = pk2(v[0], v[1]); o.y = pk2(v[2], v[3]); o.z = pk2(v[4], v[5]); o.w = pk2(v[6], v[7]); *(u32x4*)(base + (L + p0)) = o; }
.LBB0_302:
	v_add_u32_e32 v108, 0x80, v176
	v_and_b32_e32 v107, 0x3cf, v108
	v_cvt_f32_u32_e32 v106, v107
	v_or_b32_e32 v102, s71, v115
	v_ashrrev_i32_e32 v103, 31, v102
	v_lshlrev_b64 v[116:117], v80, v[102:103]
	v_mul_f32_e32 v106, 0x3a802008, v106
	v_fmamk_f32 v106, v106, 0x41447cbd, v219
	v_mul_f32_e32 v109, v142, v106
	v_lshl_add_u64 v[116:117], v[116:117], 1, v[132:133]
	v_mul_f32_e32 v109, 0x3fb8aa3b, v109
	v_cvt_pk_bf16_f32 v101, v104, v105
	v_lshl_add_u64 v[104:105], v[112:113], 1, v[116:117]
	v_exp_f32_e32 v112, v109
	v_mul_f32_e64 v109, v106, -v141
	v_mul_f32_e32 v109, 0x3fb8aa3b, v109
	v_exp_f32_e32 v109, v109
	v_lshl_add_u64 v[146:147], v[148:149], 0, v[104:105]
	flat_store_dwordx2 v[104:105], v[100:101] offset:8
	flat_store_dword v[104:105], v99 offset:4
	flat_store_short_d16_hi v[104:105], v98 offset:2
	flat_store_short v[146:147], v98
	v_mul_f32_e32 v113, v109, v112
	s_nop 0
	v_mul_f32_e32 v100, v109, v113
	v_and_b32_e32 v98, 0x400, v108
	v_mul_f32_e32 v101, v109, v100
	v_cmp_ne_u32_e64 s[10:11], 0, v98
	v_pk_mul_f32 v[98:99], v[100:101], v[96:97]
	v_mul_f32_e32 v96, v109, v101
	v_mul_f32_e32 v97, v109, v96
	v_pk_mul_f32 v[100:101], v[96:97], v[90:91]
	v_mul_f32_e32 v90, v109, v97
	v_mul_f32_e32 v91, v109, v90
	v_pk_mul_f32 v[94:95], v[112:113], v[94:95]
	v_pk_mul_f32 v[96:97], v[90:91], v[92:93]
	s_and_saveexec_b64 s[0:1], s[10:11]
	s_xor_b64 s[0:1], exec, s[0:1]
	v_cvt_pk_bf16_f32 v90, v94, v95
	v_cvt_pk_bf16_f32 v91, v98, v99
	v_cvt_pk_bf16_f32 v92, v100, v101
	s_or_saveexec_b64 s[0:1], s[0:1]
	v_mov_b64_e32 v[104:105], v[128:129]
	s_xor_b64 exec, exec, s[0:1]
	v_pk_mov_b32 v[90:91], v[96:97], v[96:97] op_sel:[1,0]
	v_pk_mov_b32 v[92:93], v[100:101], v[100:101] op_sel:[1,0]
	v_cvt_pk_bf16_f32 v90, v90, v91
	v_cvt_pk_bf16_f32 v91, v92, v93
	v_pk_mov_b32 v[92:93], v[98:99], v[98:99] op_sel:[1,0]
	v_mov_b64_e32 v[104:105], v[130:131]
	v_cvt_pk_bf16_f32 v92, v92, v93
	v_mov_b32_e32 v96, v95
	v_mov_b32_e32 v97, v94
	s_or_b64 exec, exec, s[0:1]
	v_ashrrev_i32_e32 v93, 1, v108
	v_and_b32_e32 v99, 0xfffffc00, v93
	v_or_b32_e32 v94, v99, v107
	v_ashrrev_i32_e32 v95, 31, v94
	v_lshlrev_b64 v[100:101], v80, v[94:95]
	v_lshl_add_u64 v[100:101], v[100:101], 1, v[132:133]
	v_cvt_pk_bf16_f32 v93, v96, v97
	v_lshl_add_u64 v[96:97], v[104:105], 1, v[100:101]
	v_or_b32_e32 v100, 16, v107
	v_lshl_add_u64 v[146:147], v[148:149], 0, v[96:97]
	flat_store_dwordx2 v[96:97], v[92:93] offset:8
	flat_store_dword v[96:97], v91 offset:4
	flat_store_short_d16_hi v[96:97], v90 offset:2
	flat_store_short v[146:147], v90
	s_nop 1
	v_cvt_f32_u32_e32 v90, v100
	v_mul_f32_e32 v90, 0x3a802008, v90
	v_fmamk_f32 v98, v90, 0x41447cbd, v219
	v_mul_f32_e32 v90, v142, v98
	v_mul_f32_e64 v91, v98, -v141
	v_mul_f32_e32 v90, 0x3fb8aa3b, v90
	v_mul_f32_e32 v91, 0x3fb8aa3b, v91
	v_exp_f32_e32 v90, v90
	v_exp_f32_e32 v96, v91
	s_nop 0
	v_mul_f32_e32 v91, v96, v90
	v_mul_f32_e32 v92, v96, v91
	v_mul_f32_e32 v93, v96, v92
	v_pk_mul_f32 v[86:87], v[90:91], v[86:87]
	v_pk_mul_f32 v[90:91], v[92:93], v[88:89]
	v_mul_f32_e32 v88, v96, v93
	v_mul_f32_e32 v89, v96, v88
	v_pk_mul_f32 v[92:93], v[88:89], v[82:83]
	v_mul_f32_e32 v82, v96, v89
	v_mul_f32_e32 v83, v96, v82
	v_pk_mul_f32 v[88:89], v[82:83], v[84:85]
	s_and_saveexec_b64 s[0:1], s[10:11]
	s_xor_b64 s[0:1], exec, s[0:1]
	v_cvt_pk_bf16_f32 v82, v86, v87
	v_cvt_pk_bf16_f32 v83, v90, v91
	v_cvt_pk_bf16_f32 v84, v92, v93
	s_or_saveexec_b64 s[0:1], s[0:1]
	v_mov_b64_e32 v[96:97], v[128:129]
	s_xor_b64 exec, exec, s[0:1]
	v_pk_mov_b32 v[82:83], v[88:89], v[88:89] op_sel:[1,0]
	v_pk_mov_b32 v[84:85], v[92:93], v[92:93] op_sel:[1,0]
	v_cvt_pk_bf16_f32 v82, v82, v83
	v_cvt_pk_bf16_f32 v83, v84, v85
	v_pk_mov_b32 v[84:85], v[90:91], v[90:91] op_sel:[1,0]
	v_mov_b64_e32 v[96:97], v[130:131]
	v_cvt_pk_bf16_f32 v84, v84, v85
	v_mov_b32_e32 v88, v87
	v_mov_b32_e32 v89, v86
	s_or_b64 exec, exec, s[0:1]
	v_or_b32_e32 v86, v100, v99
	v_ashrrev_i32_e32 v87, 31, v86
	v_lshlrev_b64 v[90:91], v80, v[86:87]
	v_lshl_add_u64 v[90:91], v[90:91], 1, v[132:133]
	v_cvt_pk_bf16_f32 v85, v88, v89
	v_lshl_add_u64 v[88:89], v[96:97], 1, v[90:91]
	v_or_b32_e32 v91, 32, v107
	v_lshl_add_u64 v[146:147], v[148:149], 0, v[88:89]
	flat_store_dwordx2 v[88:89], v[84:85] offset:8
	flat_store_dword v[88:89], v83 offset:4
	flat_store_short_d16_hi v[88:89], v82 offset:2
	flat_store_short v[146:147], v82
	s_nop 1
	v_cvt_f32_u32_e32 v82, v91
	v_mul_f32_e32 v82, 0x3a802008, v82
	v_fmamk_f32 v90, v82, 0x41447cbd, v219
	v_mul_f32_e32 v82, v142, v90
	v_mul_f32_e64 v83, v90, -v141
	v_mul_f32_e32 v82, 0x3fb8aa3b, v82
	v_mul_f32_e32 v83, 0x3fb8aa3b, v83
	v_exp_f32_e32 v82, v82
	v_exp_f32_e32 v88, v83
	s_nop 0
	v_mul_f32_e32 v83, v88, v82
	v_mul_f32_e32 v84, v88, v83
	v_mul_f32_e32 v85, v88, v84
	v_pk_mul_f32 v[76:77], v[82:83], v[76:77]
	v_pk_mul_f32 v[82:83], v[84:85], v[78:79]
	v_mul_f32_e32 v78, v88, v85
	v_mul_f32_e32 v79, v88, v78
	v_pk_mul_f32 v[84:85], v[78:79], v[72:73]
	v_mul_f32_e32 v72, v88, v79
	v_mul_f32_e32 v73, v88, v72
; __device__ __forceinline__ unsigned pk2(float lo, float hi) { const f32x2_t f = {lo, hi}; const bf16x2_t b = __builtin_convertvector(f, bf16x2_t); return __builtin_bit_cast(unsigned, b); }
;   __device__ __forceinline__ void operator()(const f32x4 (&acc)[2][2][4][2], const pg8::Unit& u, int wr, int wc, int fr, int fq) const {
;     ...
;         const int pr = col0 + bj * 128; const int L = pr < 2048 ? 2048 : 16384; const int p0 = pr < 2048 ? pr : pr - 2048;
;         u16* G = (u16*)(ws + (L == 2048 ? O_G2K : O_G16K));
;         const float tinv = 1.0f / (float)(L - 1);
; #pragma unroll
;         for (int ai = 0; ai < 2; ++ai)
; #pragma unroll
;           for (int m = 0; m < 4; ++m) {
;             const int fc = row0 + ai * 128 + m * 16; const int order = fc >> 11, dir = (fc >> 10) & 1, c = fc & 1023;
;             const float dl = dmin + (dmax - dmin) * ((float)c * (1.0f / 1023.0f));
;             float v[8]; float dk = __expf(-(float)p0 * tinv * dl); const float dstep = __expf(-tinv * dl);
; #pragma unroll
;             for (int e = 0; e < 8; ++e) { v[e] = acc[ai][bj][m][e >> 2][e & 3] * dk; dk *= dstep; }
;             u16* base = G + (size_t)(order * 1024 + c) * (size_t)(2 * L);
;             u32x4 o;
;             if (dir == 0) { o.x = pk2(v[7], v[6]); o.y = pk2(v[5], v[4]); o.z = pk2(v[3], v[2]); o.w = pk2(v[1], v[0]); *(u32x4*)(base + (L - 8 - p0)) = o; }
;             else { o.x = pk2(v[0], v[1]); o.y = pk2(v[2], v[3]); o.z = pk2(v[4], v[5]); o.w = pk2(v[6], v[7]); *(u32x4*)(base + (L + p0)) = o; }
	v_pk_mul_f32 v[78:79], v[72:73], v[74:75]
	s_and_saveexec_b64 s[0:1], s[10:11]
	s_xor_b64 s[0:1], exec, s[0:1]
	v_cvt_pk_bf16_f32 v72, v76, v77
	v_cvt_pk_bf16_f32 v73, v82, v83
	v_cvt_pk_bf16_f32 v74, v84, v85
	s_or_saveexec_b64 s[0:1], s[0:1]
	v_mov_b64_e32 v[88:89], v[128:129]
	s_xor_b64 exec, exec, s[0:1]
	v_pk_mov_b32 v[72:73], v[78:79], v[78:79] op_sel:[1,0]
	v_pk_mov_b32 v[74:75], v[84:85], v[84:85] op_sel:[1,0]
	v_cvt_pk_bf16_f32 v72, v72, v73
	v_cvt_pk_bf16_f32 v73, v74, v75
	v_pk_mov_b32 v[74:75], v[82:83], v[82:83] op_sel:[1,0]
	v_mov_b64_e32 v[88:89], v[130:131]
	v_cvt_pk_bf16_f32 v74, v74, v75
	v_mov_b32_e32 v78, v77
	v_mov_b32_e32 v79, v76
	s_or_b64 exec, exec, s[0:1]
	v_or_b32_e32 v76, v91, v99
	v_ashrrev_i32_e32 v77, 31, v76
	v_lshlrev_b64 v[82:83], v80, v[76:77]
	v_lshl_add_u64 v[82:83], v[82:83], 1, v[132:133]
	v_cvt_pk_bf16_f32 v75, v78, v79
	v_lshl_add_u64 v[78:79], v[88:89], 1, v[82:83]
	v_lshl_add_u64 v[146:147], v[148:149], 0, v[78:79]
	flat_store_dwordx2 v[78:79], v[74:75] offset:8
	flat_store_dword v[78:79], v73 offset:4
	flat_store_short_d16_hi v[78:79], v72 offset:2
	flat_store_short v[146:147], v72
	v_or_b32_e32 v79, 48, v107
	s_nop 0
	v_cvt_f32_u32_e32 v72, v79
	v_mul_f32_e32 v72, 0x3a802008, v72
	v_fmamk_f32 v78, v72, 0x41447cbd, v219
	v_mul_f32_e32 v72, v142, v78
	v_mul_f32_e64 v73, v78, -v141
	v_mul_f32_e32 v72, 0x3fb8aa3b, v72
	v_mul_f32_e32 v73, 0x3fb8aa3b, v73
	v_exp_f32_e32 v72, v72
	v_exp_f32_e32 v82, v73
	s_nop 0
	v_mul_f32_e32 v73, v82, v72
	v_mul_f32_e32 v74, v82, v73
	v_mul_f32_e32 v75, v82, v74
	v_pk_mul_f32 v[68:69], v[72:73], v[68:69]
	v_pk_mul_f32 v[72:73], v[74:75], v[70:71]
	v_mul_f32_e32 v70, v82, v75
	v_mul_f32_e32 v71, v82, v70
	v_pk_mul_f32 v[74:75], v[70:71], v[64:65]
	v_mul_f32_e32 v64, v82, v71
	v_mul_f32_e32 v65, v82, v64
	v_pk_mul_f32 v[70:71], v[64:65], v[66:67]
	s_and_saveexec_b64 s[0:1], s[10:11]
	s_xor_b64 s[0:1], exec, s[0:1]
	v_cvt_pk_bf16_f32 v64, v68, v69
	v_cvt_pk_bf16_f32 v65, v72, v73
	v_cvt_pk_bf16_f32 v66, v74, v75
	s_andn2_saveexec_b64 s[0:1], s[0:1]
	v_pk_mov_b32 v[64:65], v[70:71], v[70:71] op_sel:[1,0]
	v_pk_mov_b32 v[66:67], v[74:75], v[74:75] op_sel:[1,0]
	v_cvt_pk_bf16_f32 v64, v64, v65
	v_cvt_pk_bf16_f32 v65, v66, v67
	v_pk_mov_b32 v[66:67], v[72:73], v[72:73] op_sel:[1,0]
	v_mov_b64_e32 v[128:129], v[130:131]
	v_cvt_pk_bf16_f32 v66, v66, v67
	v_mov_b32_e32 v70, v69
	v_mov_b32_e32 v71, v68
	s_or_b64 exec, exec, s[0:1]
	v_or_b32_e32 v68, v79, v99
	v_ashrrev_i32_e32 v69, 31, v68
	v_lshlrev_b64 v[72:73], v80, v[68:69]
	v_lshl_add_u64 v[72:73], v[72:73], 1, v[132:133]
	v_cvt_pk_bf16_f32 v67, v70, v71
	v_lshl_add_u64 v[70:71], v[128:129], 1, v[72:73]
	v_lshl_add_u64 v[146:147], v[148:149], 0, v[70:71]
	flat_store_dwordx2 v[70:71], v[66:67] offset:8
	flat_store_dword v[70:71], v65 offset:4
	flat_store_short_d16_hi v[70:71], v64 offset:2
	flat_store_short v[146:147], v64
	s_nop 1
	v_or_b32_e32 v64, 0x80, v174
	v_cmp_gt_i32_e64 s[0:1], s94, v64
	v_add_u32_e32 v65, 0xfffff880, v174
	s_mov_b64 s[94:95], -1
	v_cndmask_b32_e64 v74, v226, v227, s[0:1]
	v_cndmask_b32_e64 v75, v65, v64, s[0:1]
	v_add_u32_e32 v64, -1, v74
	v_cvt_f32_u32_e32 v64, v64
	v_div_scale_f32 v65, s[72:73], v64, v64, 1.0
	v_rcp_f32_e32 v66, v65
	s_nop 0
	v_fma_f32 v67, -v65, v66, 1.0
	v_fmac_f32_e32 v66, v67, v66
	v_div_scale_f32 v67, vcc, 1.0, v64, 1.0
	v_mul_f32_e32 v70, v67, v66
	v_fma_f32 v71, -v65, v70, v67
	v_fmac_f32_e32 v70, v71, v66
	v_fma_f32 v65, -v65, v70, v67
	v_div_fmas_f32 v65, v65, v66, v70
	v_div_fixup_f32 v79, v65, v64, 1.0
	v_cvt_f32_i32_e32 v64, v75
	s_and_b64 vcc, exec, s[12:13]
	v_mul_f32_e64 v82, v79, -v64
	v_mul_f32_e32 v64, v140, v82
	v_mul_f32_e32 v64, 0x3fb8aa3b, v64
	v_exp_f32_e32 v66, v64
	v_mul_f32_e64 v64, v140, -v79
	v_mul_f32_e32 v64, 0x3fb8aa3b, v64
	v_exp_f32_e32 v80, v64
	s_nop 0
	v_mul_f32_e32 v67, v80, v66
	v_pk_mul_f32 v[64:65], v[66:67], v[60:61]
	v_mul_f32_e32 v60, v80, v67
	v_mul_f32_e32 v61, v80, v60
	v_pk_mul_f32 v[70:71], v[60:61], v[62:63]
	v_mul_f32_e32 v60, v80, v61
	v_mul_f32_e32 v61, v80, v60
	v_pk_mul_f32 v[72:73], v[60:61], v[56:57]
	v_mul_f32_e32 v56, v80, v61
	v_mul_f32_e32 v57, v80, v56
	v_pk_mul_f32 v[66:67], v[56:57], v[58:59]
	s_cbranch_vccnz .LBB0_320
	v_cvt_pk_bf16_f32 v56, v64, v65
	v_cvt_pk_bf16_f32 v57, v70, v71
	v_cvt_pk_bf16_f32 v58, v72, v73
	s_mov_b64 s[94:95], 0
.LBB0_320:
	v_add_u32_e32 v60, v74, v75
	v_add_u32_e32 v60, -1, v60
	v_sub_u32_e32 v59, v74, v75
	v_ashrrev_i32_e32 v61, 31, v60
	v_add_u32_e32 v62, -8, v59
	v_ashrrev_i32_e32 v63, 31, v62
	s_andn2_b64 vcc, exec, s[94:95]
	v_mov_b64_e32 v[74:75], v[60:61]
	s_cbranch_vccnz .LBB0_322
	v_pk_mov_b32 v[56:57], v[66:67], v[66:67] op_sel:[1,0]
	v_pk_mov_b32 v[58:59], v[72:73], v[72:73] op_sel:[1,0]
	v_cvt_pk_bf16_f32 v56, v56, v57
	v_cvt_pk_bf16_f32 v57, v58, v59
	v_pk_mov_b32 v[58:59], v[70:71], v[70:71] op_sel:[1,0]
	v_mov_b64_e32 v[74:75], v[62:63]
	v_cvt_pk_bf16_f32 v58, v58, v59
	v_mov_b32_e32 v66, v65
	v_mov_b32_e32 v67, v64

; #define CONV_STOREWIN(t) do { LAS unsigned char* wd_ = Wn + ((((t) >> 2) & 1) * CONV_GRP + ((t) & 3)) * WIN_BYTES + wdo; _Pragma("unroll") for (int q = 0; q < 8; ++q) LAUNDER_V(wl[q]); _Pragma("unroll") for (int q = 0; q < 4; ++q) \
;       *(LAS unsigned*)(wd_ + 128 * q) = wl[2 * q] | (wl[2 * q + 1] << 16); } while (0)
; __device__ __forceinline__ void conv_item(const Params& P, int slice, int item, LAS unsigned char* lds) {
;     ...
;     { unsigned w4[CONV_GRP][8];
; #pragma unroll
;       for (int t0 = 0; t0 < CONV_GRP; ++t0) { CONV_LOADWIN(dmin + t0);
; #pragma unroll
;         for (int q = 0; q < 8; ++q) w4[t0][q] = wl[q]; }
;       __builtin_amdgcn_sched_barrier(0);
; #pragma unroll
;       for (int t0 = 0; t0 < CONV_GRP; ++t0) {
; #pragma unroll
;         for (int q = 0; q < 8; ++q) wl[q] = w4[t0][q];
;         CONV_STOREWIN(t0); }
;     }
.LBB0_387:
	s_add_i32 s6, s17, s12
	s_ashr_i32 s7, s6, 31
	s_lshl_b64 s[8:9], s[6:7], s98
	s_lshl_b64 s[8:9], s[8:9], 1
	s_add_u32 s8, s13, s8
	s_addc_u32 s9, s22, s9
	v_lshl_add_u32 v0, v249, 1, v227
	global_load_dword v10, v0, s[8:9] offset:-1024
	global_load_dword v11, v0, s[8:9] offset:-896
	global_load_dword v12, v0, s[8:9] offset:-768
	global_load_dword v13, v0, s[8:9] offset:-640
	global_load_dword v14, v0, s[8:9] offset:-1280
	global_load_dword v15, v0, s[8:9] offset:-1152
	global_load_dword v16, v0, s[8:9] offset:-1024
	global_load_dword v17, v0, s[8:9] offset:-896
	global_load_dword v18, v0, s[8:9] offset:-1536
	global_load_dword v19, v0, s[8:9] offset:-1408
	global_load_dword v20, v0, s[8:9] offset:-1280
	global_load_dword v21, v0, s[8:9] offset:-1152
	global_load_dword v22, v0, s[8:9] offset:-1792
	global_load_dword v23, v0, s[8:9] offset:-1664
	global_load_dword v24, v0, s[8:9] offset:-1536
	global_load_dword v25, v0, s[8:9] offset:-1408
	v_add_u32_e32 v1, 0x1000, v157
	v_add_u32_e32 v2, 0x2000, v157
	v_add_u32_e32 v3, 0x3000, v157
	v_add_u32_e32 v4, 0x3400, v157
	s_waitcnt vmcnt(12)
	ds_write2_b32 v157, v10, v11 offset1:32
	ds_write2_b32 v157, v12, v13 offset0:64 offset1:96
	s_waitcnt vmcnt(8)
	ds_write2_b32 v1, v14, v15 offset0:64 offset1:96
	ds_write2_b32 v1, v16, v17 offset0:128 offset1:160
	s_waitcnt vmcnt(4)
	ds_write2_b32 v2, v18, v19 offset0:128 offset1:160
	ds_write2_b32 v2, v20, v21 offset0:192 offset1:224
	s_waitcnt vmcnt(0)
	ds_write2_b32 v3, v22, v23 offset0:192 offset1:224
	s_andn2_b64 vcc, exec, s[4:5]
	ds_write2_b32 v4, v24, v25 offset1:32
	s_waitcnt lgkmcnt(0)
	s_barrier
	s_cbranch_vccnz .LBB0_396
	s_mov_b32 s16, 0
	v_mov_b32_e32 v8, v249
	s_branch .LBB0_390

; #define CONV_HEAD() const int step = d - dmin; if (step + CONV_GRP < nsteps) CONV_LOADWIN(d + CONV_GRP); __builtin_amdgcn_sched_barrier(0)
; #define CONV_TAIL() if (step + CONV_GRP < nsteps) CONV_STOREWIN(step + CONV_GRP); if ((step & 1) == 1 || step + 1 == nsteps) __syncthreads()
; __device__ __forceinline__ void conv_item(const Params& P, int slice, int item, LAS unsigned char* lds) {
;     ...
;     for (int d = dmin; d < lo0; ++d) { CONV_HEAD(); CONV_TAIL(); }
.LBB0_390:
	s_add_i32 s17, s16, 4
	s_cmp_lt_i32 s17, s87
	s_cselect_b64 s[10:11], -1, 0
	s_cmp_ge_i32 s17, s87
	s_cbranch_scc1 .LBB0_392
	v_lshl_add_u32 v240, v8, 1, v227
	global_load_dword v230, v240, s[8:9] offset:-2048
	global_load_dword v231, v240, s[8:9] offset:-1920
	global_load_dword v238, v240, s[8:9] offset:-1792
	global_load_dword v239, v240, s[8:9] offset:-1664
.LBB0_392:
	s_andn2_b64 vcc, exec, s[10:11]
	s_cbranch_vccnz .LBB0_394
	s_and_b32 s10, s17, 4
	s_and_b32 s11, s16, 3
	s_or_b32 s10, s10, s11
	s_mulk_i32 s10, 0x1100
	v_add_u32_e32 v9, s10, v157
	s_waitcnt vmcnt(0)
	ds_write2_b32 v9, v230, v231 offset1:32
	ds_write2_b32 v9, v238, v239 offset0:64 offset1:96

; #define LAS __attribute__((address_space(3)))
; #define CONV_HEAD() const int step = d - dmin; if (step + CONV_GRP < nsteps) CONV_LOADWIN(d + CONV_GRP); __builtin_amdgcn_sched_barrier(0)
; #define CONV_TAIL() if (step + CONV_GRP < nsteps) CONV_STOREWIN(step + CONV_GRP); if ((step & 1) == 1 || step + 1 == nsteps) __syncthreads()
; #define CONV_DS(x) ({ int t_ = (x); LAUNDER_S(t_); t_; })
; __device__ __forceinline__ void conv_item(const Params& P, int slice, int item, LAS unsigned char* lds) {
;     ...
;     for (int d = dmin; d < lo0; ++d) { CONV_HEAD(); CONV_TAIL(); }
;     {
;       const LAS unsigned char* wb = CONV_WB(lo0 - dmin); const LAS unsigned char* bp0 = CONV_BPH(0, 0, lo0); const LAS unsigned char* bp1 = CONV_BPH(0, 1, lo0);
; #pragma unroll
;       for (int k = 0; k < 10; ++k) fa[k] = *(const LAS bf16x8*)(wb + 32 * (k - 3));
; #pragma unroll
;       for (int ks = 0; ks < 4; ++ks) { fb[ks] = *(const LAS bf16x8*)(bp0 + 64 * ks); fb[4 + ks] = *(const LAS bf16x8*)(bp1 + 64 * ks); }
;     }
;     const int hw = 16 >> nbsh;
;     ...
;     for (int d = CONV_DS(lo0); d < lo0 + hw; ++d) { CONV_HEADT(); CONV_TILESTEP(0, CONV_BPH(0, 0, d + 1), CONV_BPH(0, 1, d + 1), 1, CONV_WB(step + 1), 1, 1); CONV_TAIL(); }
.LBB0_399:
	s_add_i32 s68, s61, s16
	s_add_i32 s17, s68, -1
	s_setprio 1
	v_lshl_add_u32 v240, v40, 1, v227
	global_load_dword v230, v240, s[8:9] offset:-2048
	global_load_dword v231, v240, s[8:9] offset:-1920
	global_load_dword v238, v240, s[8:9] offset:-1792
	global_load_dword v239, v240, s[8:9] offset:-1664
	v_add_u32_e32 v44, s30, v41
	s_and_b32 s0, s68, 7
	s_mulk_i32 s0, 0x1100
	s_waitcnt lgkmcnt(1)
	v_mfma_f32_16x16x32_bf16 v[12:15], v[88:91], v[144:147], v[12:15]
	v_mfma_f32_16x16x32_bf16 v[4:7], v[72:75], v[144:147], v[16:19]
	v_mfma_f32_16x16x32_bf16 v[16:19], v[64:67], v[144:147], v[20:23]
	v_mfma_f32_16x16x32_bf16 v[8:11], v[76:79], v[144:147], v[8:11]
	v_add_u32_e32 v51, s0, v243
	s_waitcnt lgkmcnt(6)
	v_mfma_f32_16x16x32_bf16 v[12:15], v[72:75], v[140:143], v[12:15]
	ds_read_b128 v[72:75], v51 offset:256
	v_mov_b32_e32 v45, s29
	v_cmp_gt_u32_e32 vcc, s61, v41
	v_cmp_gt_u32_e64 s[0:1], s61, v44
	s_nop 0
	v_cndmask_b32_e32 v50, v45, v43, vcc
	s_nop 0
	v_cndmask_b32_e64 v52, v45, v42, s[0:1]
	v_mfma_f32_16x16x32_bf16 v[4:7], v[56:59], v[140:143], v[4:7]
	v_mfma_f32_16x16x32_bf16 v[16:19], v[60:63], v[140:143], v[16:19]
	s_waitcnt lgkmcnt(4)
	v_mfma_f32_16x16x32_bf16 v[4:7], v[28:31], v[136:139], v[4:7]
	ds_read_b128 v[76:79], v51 offset:160
	ds_read_b128 v[88:91], v51 offset:192
	s_waitcnt lgkmcnt(3)
	ds_read_b128 v[116:119], v52 offset:192
	v_mfma_f32_16x16x32_bf16 v[20:23], v[24:27], v[136:139], v[16:19]
	s_nop 2
	v_mfma_f32_16x16x32_bf16 v[16:19], v[32:35], v[132:135], v[4:7]
	v_mfma_f32_16x16x32_bf16 v[8:11], v[64:67], v[140:143], v[8:11]
	v_mfma_f32_16x16x32_bf16 v[12:15], v[56:59], v[136:139], v[12:15]
	v_mfma_f32_16x16x32_bf16 v[8:11], v[60:63], v[136:139], v[8:11]
	ds_read_b128 v[136:139], v50 offset:128
	v_mfma_f32_16x16x32_bf16 v[12:15], v[28:31], v[132:135], v[12:15]
	v_mfma_f32_16x16x32_bf16 v[20:23], v[36:39], v[132:135], v[20:23]
	v_mfma_f32_16x16x32_bf16 v[8:11], v[24:27], v[132:135], v[8:11]
	ds_read_b128 v[32:35], v51 offset:448
	ds_read_b128 v[28:31], v51 offset:384
	ds_read_b128 v[36:39], v51 offset:416
	ds_read_b128 v[24:27], v51 offset:352
	ds_read_b128 v[60:63], v51 offset:288
	ds_read_b128 v[56:59], v51 offset:320
	ds_read_b128 v[132:135], v50 offset:192
	ds_read_b128 v[120:123], v52 offset:128
	ds_read_b128 v[140:143], v50 offset:64
	ds_read_b128 v[124:127], v52 offset:64
	ds_read_b128 v[64:67], v51 offset:224
	ds_read_b128 v[144:147], v50
	ds_read_b128 v[128:131], v52
	s_setprio 0
	s_add_i32 s68, s68, 3
	s_cmp_ge_i32 s68, s87
	s_cbranch_scc1 .LBB0_401
	s_and_b32 s0, s68, 4
	s_and_b32 s1, s17, 3
	s_or_b32 s0, s0, s1
	s_mulk_i32 s0, 0x1100
	v_add_u32_e32 v44, s0, v157
	s_waitcnt vmcnt(0)
	ds_write2_b32 v44, v230, v231 offset1:32
	ds_write2_b32 v44, v238, v239 offset0:64 offset1:96

; #define LAS __attribute__((address_space(3)))
; #define CONV_HEAD() const int step = d - dmin; if (step + CONV_GRP < nsteps) CONV_LOADWIN(d + CONV_GRP); __builtin_amdgcn_sched_barrier(0)
; #define CONV_TAIL() if (step + CONV_GRP < nsteps) CONV_STOREWIN(step + CONV_GRP); if ((step & 1) == 1 || step + 1 == nsteps) __syncthreads()
; #define CONV_DS(x) ({ int t_ = (x); LAUNDER_S(t_); t_; })
; __device__ __forceinline__ void conv_item(const Params& P, int slice, int item, LAS unsigned char* lds) {
;     ...
;     for (int d = dmin; d < lo0; ++d) { CONV_HEAD(); CONV_TAIL(); }
;     {
;       const LAS unsigned char* wb = CONV_WB(lo0 - dmin); const LAS unsigned char* bp0 = CONV_BPH(0, 0, lo0); const LAS unsigned char* bp1 = CONV_BPH(0, 1, lo0);
; #pragma unroll
;       for (int k = 0; k < 10; ++k) fa[k] = *(const LAS bf16x8*)(wb + 32 * (k - 3));
; #pragma unroll
;       for (int ks = 0; ks < 4; ++ks) { fb[ks] = *(const LAS bf16x8*)(bp0 + 64 * ks); fb[4 + ks] = *(const LAS bf16x8*)(bp1 + 64 * ks); }
;     }
;     const int hw = 16 >> nbsh;
;     ...
;     for (int d = CONV_DS(lo0); d < lo0 + hw; ++d) { CONV_HEADT(); CONV_TILESTEP(0, CONV_BPH(0, 0, d + 1), CONV_BPH(0, 1, d + 1), 1, CONV_WB(step + 1), 1, 1); CONV_TAIL(); }
;     for (int d = CONV_DS(lo0 + hw); d < lo1; ++d) { CONV_HEADT(); CONV_TILESTEP(0, CONV_BPH(0, 0, d + 1), CONV_BPH(0, 1, d + 1), 1, CONV_WB(step + 1), 3, 1); CONV_TAIL(); }
.LBB0_407:
	s_add_i32 s68, s61, s16
	s_add_i32 s17, s68, -1
	s_setprio 1
	v_lshl_add_u32 v240, v68, 1, v227
	global_load_dword v230, v240, s[8:9] offset:-2048
	global_load_dword v231, v240, s[8:9] offset:-1920
	global_load_dword v238, v240, s[8:9] offset:-1792
	global_load_dword v239, v240, s[8:9] offset:-1664
	v_add_u32_e32 v86, s30, v69
	s_and_b32 s0, s68, 7
	s_mulk_i32 s0, 0x1100
	s_waitcnt lgkmcnt(1)
	v_mfma_f32_16x16x32_bf16 v[0:3], v[72:75], v[144:147], v[16:19]
	v_mfma_f32_16x16x32_bf16 v[4:7], v[64:67], v[144:147], v[20:23]
	v_mfma_f32_16x16x32_bf16 v[12:15], v[88:91], v[144:147], v[12:15]
	v_mfma_f32_16x16x32_bf16 v[8:11], v[76:79], v[144:147], v[8:11]
	s_waitcnt lgkmcnt(0)
	v_mfma_f32_16x16x32_bf16 v[16:19], v[72:75], v[128:131], v[52:55]
	v_mfma_f32_16x16x32_bf16 v[0:3], v[56:59], v[140:143], v[0:3]
	v_mfma_f32_16x16x32_bf16 v[16:19], v[56:59], v[124:127], v[16:19]
	v_mfma_f32_16x16x32_bf16 v[0:3], v[28:31], v[136:139], v[0:3]
	v_mfma_f32_16x16x32_bf16 v[20:23], v[28:31], v[120:123], v[16:19]
	v_mfma_f32_16x16x32_bf16 v[16:19], v[32:35], v[132:135], v[0:3]
	v_mfma_f32_16x16x32_bf16 v[52:55], v[32:35], v[116:119], v[20:23]
	v_mfma_f32_16x16x32_bf16 v[20:23], v[64:67], v[128:131], v[48:51]
	s_nop 3
	v_mfma_f32_16x16x32_bf16 v[44:47], v[88:91], v[128:131], v[44:47]
	v_mfma_f32_16x16x32_bf16 v[12:15], v[72:75], v[140:143], v[12:15]
	v_mfma_f32_16x16x32_bf16 v[44:47], v[72:75], v[124:127], v[44:47]
	v_mfma_f32_16x16x32_bf16 v[40:43], v[76:79], v[128:131], v[40:43]
	v_mov_b32_e32 v72, s29
	v_mfma_f32_16x16x32_bf16 v[12:15], v[56:59], v[136:139], v[12:15]
	v_mfma_f32_16x16x32_bf16 v[44:47], v[56:59], v[120:123], v[44:47]
	v_mfma_f32_16x16x32_bf16 v[2:5], v[60:63], v[140:143], v[4:7]
	v_mfma_f32_16x16x32_bf16 v[20:23], v[60:63], v[124:127], v[20:23]
	v_mfma_f32_16x16x32_bf16 v[2:5], v[24:27], v[136:139], v[2:5]
	v_mfma_f32_16x16x32_bf16 v[48:51], v[24:27], v[120:123], v[20:23]
	v_mfma_f32_16x16x32_bf16 v[20:23], v[36:39], v[132:135], v[2:5]
	v_mfma_f32_16x16x32_bf16 v[2:5], v[64:67], v[140:143], v[8:11]
	v_mfma_f32_16x16x32_bf16 v[6:9], v[64:67], v[124:127], v[40:43]
	v_mfma_f32_16x16x32_bf16 v[2:5], v[60:63], v[136:139], v[2:5]
	v_mfma_f32_16x16x32_bf16 v[40:43], v[60:63], v[120:123], v[6:9]
	v_mfma_f32_16x16x32_bf16 v[8:11], v[24:27], v[132:135], v[2:5]
	s_nop 5
	v_cmp_gt_u32_e32 vcc, s61, v69
	s_nop 0
	s_nop 0
	v_cndmask_b32_e32 v82, v72, v71, vcc
	ds_read_b128 v[136:139], v82 offset:128
	v_add_u32_e32 v87, s0, v243
	v_cmp_gt_u32_e64 s[0:1], s61, v86
	s_nop 1
	v_cndmask_b32_e64 v74, v72, v70, s[0:1]
	ds_read_b128 v[88:91], v87 offset:192
	ds_read_b128 v[124:127], v74 offset:64
	ds_read_b128 v[120:123], v74 offset:128
	ds_read_b128 v[128:131], v74
	v_mfma_f32_16x16x32_bf16 v[44:47], v[28:31], v[116:119], v[44:47]
	v_mfma_f32_16x16x32_bf16 v[48:51], v[36:39], v[116:119], v[48:51]
	v_mfma_f32_16x16x32_bf16 v[40:43], v[24:27], v[116:119], v[40:43]
	ds_read_b128 v[116:119], v74 offset:192
	ds_read_b128 v[72:75], v87 offset:256
	ds_read_b128 v[32:35], v87 offset:448
	ds_read_b128 v[76:79], v87 offset:160
	v_mfma_f32_16x16x32_bf16 v[12:15], v[28:31], v[132:135], v[12:15]
	ds_read_b128 v[28:31], v87 offset:384
	ds_read_b128 v[144:147], v82
	ds_read_b128 v[140:143], v82 offset:64
	ds_read_b128 v[64:67], v87 offset:224
	ds_read_b128 v[36:39], v87 offset:416
	ds_read_b128 v[24:27], v87 offset:352
	ds_read_b128 v[132:135], v82 offset:192
	ds_read_b128 v[60:63], v87 offset:288
	ds_read_b128 v[56:59], v87 offset:320
	s_setprio 0
	s_add_i32 s68, s68, 3
	s_cmp_ge_i32 s68, s87
	s_cbranch_scc1 .LBB0_409
	s_and_b32 s0, s68, 4
	s_and_b32 s1, s17, 3
	s_or_b32 s0, s0, s1
	s_mulk_i32 s0, 0x1100
	v_add_u32_e32 v80, s0, v157
	s_waitcnt vmcnt(0)
	ds_write2_b32 v80, v230, v231 offset1:32
	ds_write2_b32 v80, v238, v239 offset0:64 offset1:96

; #define LAS __attribute__((address_space(3)))
; #define CONV_HEAD() const int step = d - dmin; if (step + CONV_GRP < nsteps) CONV_LOADWIN(d + CONV_GRP); __builtin_amdgcn_sched_barrier(0)
; #define CONV_TAIL() if (step + CONV_GRP < nsteps) CONV_STOREWIN(step + CONV_GRP); if ((step & 1) == 1 || step + 1 == nsteps) __syncthreads()
; #define CONV_DS(x) ({ int t_ = (x); LAUNDER_S(t_); t_; })
; #define CONV_NB1(H) ((d + 1 <= hi0) ? CONV_BPH(0, H, d + 1) : CONV_BPH(1, H, d + 1))
; __device__ __forceinline__ void conv_item(const Params& P, int slice, int item, LAS unsigned char* lds) {
;     ...
;     for (int d = dmin; d < lo0; ++d) { CONV_HEAD(); CONV_TAIL(); }
;     {
;       const LAS unsigned char* wb = CONV_WB(lo0 - dmin); const LAS unsigned char* bp0 = CONV_BPH(0, 0, lo0); const LAS unsigned char* bp1 = CONV_BPH(0, 1, lo0);
; #pragma unroll
;       for (int k = 0; k < 10; ++k) fa[k] = *(const LAS bf16x8*)(wb + 32 * (k - 3));
; #pragma unroll
;       for (int ks = 0; ks < 4; ++ks) { fb[ks] = *(const LAS bf16x8*)(bp0 + 64 * ks); fb[4 + ks] = *(const LAS bf16x8*)(bp1 + 64 * ks); }
;     }
;     const int hw = 16 >> nbsh;
;     ...
;     for (int d = CONV_DS(lo0); d < lo0 + hw; ++d) { CONV_HEADT(); CONV_TILESTEP(0, CONV_BPH(0, 0, d + 1), CONV_BPH(0, 1, d + 1), 1, CONV_WB(step + 1), 1, 1); CONV_TAIL(); }
;     for (int d = CONV_DS(lo0 + hw); d < lo1; ++d) { CONV_HEADT(); CONV_TILESTEP(0, CONV_BPH(0, 0, d + 1), CONV_BPH(0, 1, d + 1), 1, CONV_WB(step + 1), 3, 1); CONV_TAIL(); }
;     for (int d = CONV_DS(lo1); d < lo1 + hw; ++d) { CONV_HEADT(); CONV_TILESTEP(0, CONV_BPH(1, 0, d), CONV_BPH(1, 1, d), 0, Wn, 3, 1);
;       CONV_TILESTEP(1, CONV_NB1(0), CONV_NB1(1), 1, CONV_WB(step + 1), 1, 0); CONV_TAIL(); }
.LBB0_415:
	s_setprio 1
	v_lshl_add_u32 v240, v100, 1, v227
	global_load_dword v230, v240, s[8:9] offset:-2048
	global_load_dword v231, v240, s[8:9] offset:-1920
	global_load_dword v238, v240, s[8:9] offset:-1792
	global_load_dword v239, v240, s[8:9] offset:-1664
	v_add3_u32 v83, v247, s17, 1
	s_add_i32 s69, s61, s16
	s_add_i32 s68, s69, -1
	s_waitcnt lgkmcnt(1)
	v_mfma_f32_16x16x32_bf16 v[2:5], v[72:75], v[144:147], v[16:19]
	v_mfma_f32_16x16x32_bf16 v[16:19], v[64:67], v[144:147], v[20:23]
	v_mfma_f32_16x16x32_bf16 v[12:15], v[88:91], v[144:147], v[12:15]
	v_mfma_f32_16x16x32_bf16 v[6:9], v[76:79], v[144:147], v[8:11]
	s_waitcnt lgkmcnt(0)
	v_mfma_f32_16x16x32_bf16 v[20:23], v[72:75], v[128:131], v[52:55]
	v_mfma_f32_16x16x32_bf16 v[48:51], v[64:67], v[128:131], v[48:51]
	v_mfma_f32_16x16x32_bf16 v[44:47], v[88:91], v[128:131], v[44:47]
	v_mfma_f32_16x16x32_bf16 v[40:43], v[76:79], v[128:131], v[40:43]
	v_mfma_f32_16x16x32_bf16 v[52:55], v[56:59], v[140:143], v[2:5]
	v_mfma_f32_16x16x32_bf16 v[4:7], v[64:67], v[140:143], v[6:9]
	v_mfma_f32_16x16x32_bf16 v[20:23], v[56:59], v[124:127], v[20:23]
	v_mfma_f32_16x16x32_bf16 v[10:13], v[72:75], v[140:143], v[12:15]
	v_mfma_f32_16x16x32_bf16 v[48:51], v[60:63], v[124:127], v[48:51]
	v_mfma_f32_16x16x32_bf16 v[44:47], v[72:75], v[124:127], v[44:47]
	v_mfma_f32_16x16x32_bf16 v[40:43], v[64:67], v[124:127], v[40:43]
	v_mfma_f32_16x16x32_bf16 v[106:109], v[60:63], v[136:139], v[4:7]
	v_cmp_gt_u32_e32 vcc, s61, v83
	v_mov_b32_e32 v83, s29
	s_nop 0
	v_cndmask_b32_e32 v130, v83, v82, vcc
	v_mfma_f32_16x16x32_bf16 v[16:19], v[60:63], v[140:143], v[16:19]
	v_mfma_f32_16x16x32_bf16 v[52:55], v[28:31], v[136:139], v[52:55]
	v_mfma_f32_16x16x32_bf16 v[48:51], v[24:27], v[120:123], v[48:51]
	v_mfma_f32_16x16x32_bf16 v[44:47], v[56:59], v[120:123], v[44:47]
	v_mfma_f32_16x16x32_bf16 v[8:11], v[56:59], v[136:139], v[10:13]
	v_mfma_f32_16x16x32_bf16 v[12:15], v[28:31], v[132:135], v[8:11]
	v_mfma_f32_16x16x32_bf16 v[8:11], v[24:27], v[132:135], v[106:109]
	s_nop 2
	ds_read_b128 v[106:109], v130 offset:64
	v_mfma_f32_16x16x32_bf16 v[102:105], v[24:27], v[136:139], v[16:19]
	v_mfma_f32_16x16x32_bf16 v[124:127], v[28:31], v[120:123], v[20:23]
	v_mfma_f32_16x16x32_bf16 v[40:43], v[60:63], v[120:123], v[40:43]
	ds_read_b128 v[110:113], v130 offset:128
	v_mfma_f32_16x16x32_bf16 v[16:19], v[32:35], v[132:135], v[52:55]
	v_mfma_f32_16x16x32_bf16 v[20:23], v[36:39], v[132:135], v[102:105]
	ds_read_b128 v[120:123], v130 offset:192
	v_mfma_f32_16x16x32_bf16 v[52:55], v[32:35], v[116:119], v[124:127]
	v_mfma_f32_16x16x32_bf16 v[48:51], v[36:39], v[116:119], v[48:51]
	v_mfma_f32_16x16x32_bf16 v[44:47], v[28:31], v[116:119], v[44:47]
	v_mfma_f32_16x16x32_bf16 v[40:43], v[24:27], v[116:119], v[40:43]
	ds_read_b128 v[102:105], v130
	s_setprio 0
	s_setprio 1
	s_cmp_lt_i32 s16, s26
	s_cselect_b64 vcc, -1, 0
	v_cndmask_b32_e32 v80, v247, v242, vcc
	v_add_u32_e32 v80, s17, v80
	v_cndmask_b32_e32 v101, v248, v245, vcc
	v_cmp_gt_u32_e64 s[0:1], s61, v80
	v_mad_u64_u32 v[114:115], s[70:71], v80, s85, v[156:157]
	v_add_u32_e32 v101, s17, v101
	v_cndmask_b32_e64 v80, v83, v114, s[0:1]
	v_mad_u64_u32 v[114:115], s[0:1], v101, s85, v[156:157]
	s_and_b32 s0, s69, 7
	v_cmp_gt_u32_e32 vcc, s61, v101
	s_mulk_i32 s0, 0x1100
	v_add_u32_e32 v101, s0, v243
	v_cndmask_b32_e32 v83, v83, v114, vcc
	s_waitcnt lgkmcnt(0)
	v_mfma_f32_16x16x32_bf16 v[92:95], v[72:75], v[102:105], v[92:95]
	v_mfma_f32_16x16x32_bf16 v[96:99], v[64:67], v[102:105], v[96:99]
	v_mfma_f32_16x16x32_bf16 v[84:87], v[88:91], v[102:105], v[84:87]
	v_mfma_f32_16x16x32_bf16 v[68:71], v[76:79], v[102:105], v[68:71]
	ds_read_b128 v[144:147], v80
	v_mfma_f32_16x16x32_bf16 v[92:95], v[56:59], v[106:109], v[92:95]
	v_mfma_f32_16x16x32_bf16 v[96:99], v[60:63], v[106:109], v[96:99]
	v_mfma_f32_16x16x32_bf16 v[72:75], v[72:75], v[106:109], v[84:87]
	v_mfma_f32_16x16x32_bf16 v[64:67], v[64:67], v[106:109], v[68:71]
	ds_read_b128 v[128:131], v83
	ds_read_b128 v[76:79], v101 offset:160
	ds_read_b128 v[88:91], v101 offset:192
	v_mfma_f32_16x16x32_bf16 v[68:71], v[28:31], v[110:113], v[92:95]
	v_mfma_f32_16x16x32_bf16 v[84:87], v[24:27], v[110:113], v[96:99]
	v_mfma_f32_16x16x32_bf16 v[56:59], v[56:59], v[110:113], v[72:75]
	v_mfma_f32_16x16x32_bf16 v[60:63], v[60:63], v[110:113], v[64:67]
	ds_read_b128 v[140:143], v80 offset:64
	v_mfma_f32_16x16x32_bf16 v[92:95], v[32:35], v[120:123], v[68:71]
	v_mfma_f32_16x16x32_bf16 v[96:99], v[36:39], v[120:123], v[84:87]
	v_mfma_f32_16x16x32_bf16 v[84:87], v[28:31], v[120:123], v[56:59]
	v_mfma_f32_16x16x32_bf16 v[68:71], v[24:27], v[120:123], v[60:63]
	ds_read_b128 v[124:127], v83 offset:64
	ds_read_b128 v[64:67], v101 offset:224
	ds_read_b128 v[72:75], v101 offset:256
	ds_read_b128 v[136:139], v80 offset:128
	ds_read_b128 v[120:123], v83 offset:128
	ds_read_b128 v[60:63], v101 offset:288
	ds_read_b128 v[56:59], v101 offset:320
	ds_read_b128 v[132:135], v80 offset:192
	ds_read_b128 v[116:119], v83 offset:192
	ds_read_b128 v[24:27], v101 offset:352
	ds_read_b128 v[28:31], v101 offset:384
	ds_read_b128 v[36:39], v101 offset:416
	ds_read_b128 v[32:35], v101 offset:448
	s_setprio 0
	s_add_i32 s0, s69, 3
	s_cmp_ge_i32 s0, s87
	s_cbranch_scc1 .LBB0_417
	s_and_b32 s0, s0, 4
	s_and_b32 s1, s68, 3
	s_or_b32 s0, s0, s1
	s_mulk_i32 s0, 0x1100
	v_add_u32_e32 v80, s0, v157
	s_waitcnt vmcnt(0)
	ds_write2_b32 v80, v230, v231 offset1:32
	ds_write2_b32 v80, v238, v239 offset0:64 offset1:96

; #define LAS __attribute__((address_space(3)))
; #define CONV_HEAD() const int step = d - dmin; if (step + CONV_GRP < nsteps) CONV_LOADWIN(d + CONV_GRP); __builtin_amdgcn_sched_barrier(0)
; #define CONV_TAIL() if (step + CONV_GRP < nsteps) CONV_STOREWIN(step + CONV_GRP); if ((step & 1) == 1 || step + 1 == nsteps) __syncthreads()
; #define CONV_DS(x) ({ int t_ = (x); LAUNDER_S(t_); t_; })
; #define CONV_NB1(H) ((d + 1 <= hi0) ? CONV_BPH(0, H, d + 1) : CONV_BPH(1, H, d + 1))
; __device__ __forceinline__ void conv_item(const Params& P, int slice, int item, LAS unsigned char* lds) {
;     ...
;     for (int d = dmin; d < lo0; ++d) { CONV_HEAD(); CONV_TAIL(); }
;     {
;       const LAS unsigned char* wb = CONV_WB(lo0 - dmin); const LAS unsigned char* bp0 = CONV_BPH(0, 0, lo0); const LAS unsigned char* bp1 = CONV_BPH(0, 1, lo0);
; #pragma unroll
;       for (int k = 0; k < 10; ++k) fa[k] = *(const LAS bf16x8*)(wb + 32 * (k - 3));
; #pragma unroll
;       for (int ks = 0; ks < 4; ++ks) { fb[ks] = *(const LAS bf16x8*)(bp0 + 64 * ks); fb[4 + ks] = *(const LAS bf16x8*)(bp1 + 64 * ks); }
;     }
;     const int hw = 16 >> nbsh;
;     ...
;     for (int d = CONV_DS(lo0); d < lo0 + hw; ++d) { CONV_HEADT(); CONV_TILESTEP(0, CONV_BPH(0, 0, d + 1), CONV_BPH(0, 1, d + 1), 1, CONV_WB(step + 1), 1, 1); CONV_TAIL(); }
;     for (int d = CONV_DS(lo0 + hw); d < lo1; ++d) { CONV_HEADT(); CONV_TILESTEP(0, CONV_BPH(0, 0, d + 1), CONV_BPH(0, 1, d + 1), 1, CONV_WB(step + 1), 3, 1); CONV_TAIL(); }
;     for (int d = CONV_DS(lo1); d < lo1 + hw; ++d) { CONV_HEADT(); CONV_TILESTEP(0, CONV_BPH(1, 0, d), CONV_BPH(1, 1, d), 0, Wn, 3, 1);
;       CONV_TILESTEP(1, CONV_NB1(0), CONV_NB1(1), 1, CONV_WB(step + 1), 1, 0); CONV_TAIL(); }
;     for (int d = CONV_DS(lo1 + hw); d <= hi0 - hw; ++d) { CONV_HEADT(); CONV_TILESTEP(0, CONV_BPH(1, 0, d), CONV_BPH(1, 1, d), 0, Wn, 3, 1);
;       CONV_TILESTEP(1, CONV_NB1(0), CONV_NB1(1), 1, CONV_WB(step + 1), 3, 0); CONV_TAIL(); }
.LBB0_422:
	s_add_i32 s68, s17, 1
	s_setprio 1
	v_lshl_add_u32 v240, v150, 1, v227
	global_load_dword v230, v240, s[8:9] offset:-2048
	global_load_dword v231, v240, s[8:9] offset:-1920
	global_load_dword v238, v240, s[8:9] offset:-1792
	global_load_dword v239, v240, s[8:9] offset:-1664
	v_add3_u32 v83, v247, s16, 1
	v_add3_u32 v149, v248, s16, 1
	s_add_i32 s69, s61, s17
	s_waitcnt lgkmcnt(1)
	v_mfma_f32_16x16x32_bf16 v[16:19], v[72:75], v[144:147], v[16:19]
	v_mfma_f32_16x16x32_bf16 v[20:23], v[64:67], v[144:147], v[20:23]
	v_mfma_f32_16x16x32_bf16 v[12:15], v[88:91], v[144:147], v[12:15]
	v_mfma_f32_16x16x32_bf16 v[8:11], v[76:79], v[144:147], v[8:11]
	s_waitcnt lgkmcnt(0)
	v_mfma_f32_16x16x32_bf16 v[52:55], v[72:75], v[128:131], v[52:55]
	v_mfma_f32_16x16x32_bf16 v[48:51], v[64:67], v[128:131], v[48:51]
	v_mfma_f32_16x16x32_bf16 v[44:47], v[88:91], v[128:131], v[44:47]
	v_mfma_f32_16x16x32_bf16 v[40:43], v[76:79], v[128:131], v[40:43]
	v_mfma_f32_16x16x32_bf16 v[40:43], v[64:67], v[124:127], v[40:43]
	v_mfma_f32_16x16x32_bf16 v[40:43], v[60:63], v[120:123], v[40:43]
	v_mfma_f32_16x16x32_bf16 v[40:43], v[24:27], v[116:119], v[40:43]
	v_mfma_f32_16x16x32_bf16 v[44:47], v[72:75], v[124:127], v[44:47]
	v_mfma_f32_16x16x32_bf16 v[44:47], v[56:59], v[120:123], v[44:47]
	v_mfma_f32_16x16x32_bf16 v[44:47], v[28:31], v[116:119], v[44:47]
	v_mfma_f32_16x16x32_bf16 v[48:51], v[60:63], v[124:127], v[48:51]
	v_mfma_f32_16x16x32_bf16 v[48:51], v[24:27], v[120:123], v[48:51]
	v_mfma_f32_16x16x32_bf16 v[48:51], v[36:39], v[116:119], v[48:51]
	v_mfma_f32_16x16x32_bf16 v[52:55], v[56:59], v[124:127], v[52:55]
	v_mfma_f32_16x16x32_bf16 v[52:55], v[28:31], v[120:123], v[52:55]
	v_mfma_f32_16x16x32_bf16 v[52:55], v[32:35], v[116:119], v[52:55]
	v_mov_b32_e32 v80, s29
	v_cmp_gt_u32_e32 vcc, s61, v83
	s_nop 1
	v_cndmask_b32_e32 v83, v80, v148, vcc
	v_cmp_gt_u32_e32 vcc, s61, v149
	s_nop 1
	v_cndmask_b32_e32 v149, v80, v82, vcc
	ds_read_b128 v[116:119], v149 offset:192
	v_mfma_f32_16x16x32_bf16 v[8:11], v[64:67], v[140:143], v[8:11]
	v_mfma_f32_16x16x32_bf16 v[16:19], v[56:59], v[140:143], v[16:19]
	v_mfma_f32_16x16x32_bf16 v[20:23], v[60:63], v[140:143], v[20:23]
	v_mfma_f32_16x16x32_bf16 v[12:15], v[72:75], v[140:143], v[12:15]
	v_mfma_f32_16x16x32_bf16 v[8:11], v[60:63], v[136:139], v[8:11]
	v_mfma_f32_16x16x32_bf16 v[8:11], v[24:27], v[132:135], v[8:11]
	v_mfma_f32_16x16x32_bf16 v[12:15], v[56:59], v[136:139], v[12:15]
	v_mfma_f32_16x16x32_bf16 v[12:15], v[28:31], v[132:135], v[12:15]
	v_mfma_f32_16x16x32_bf16 v[20:23], v[24:27], v[136:139], v[20:23]
	v_mfma_f32_16x16x32_bf16 v[20:23], v[36:39], v[132:135], v[20:23]
	v_mfma_f32_16x16x32_bf16 v[16:19], v[28:31], v[136:139], v[16:19]
	v_mfma_f32_16x16x32_bf16 v[16:19], v[32:35], v[132:135], v[16:19]
	ds_read_b128 v[132:135], v83 offset:192
	ds_read_b128 v[120:123], v149 offset:128
	ds_read_b128 v[136:139], v83 offset:128
	ds_read_b128 v[124:127], v149 offset:64
	ds_read_b128 v[140:143], v83 offset:64
	ds_read_b128 v[128:131], v149
	ds_read_b128 v[144:147], v83
	s_setprio 0
	s_setprio 1
	s_cmp_lt_i32 s68, s26
	s_cselect_b64 vcc, -1, 0
	v_cndmask_b32_e32 v83, v247, v242, vcc
	v_add_u32_e32 v83, s16, v83
	v_cndmask_b32_e32 v149, v248, v245, vcc
	v_cmp_gt_u32_e64 s[0:1], s61, v83
	v_mad_u64_u32 v[152:153], s[70:71], v83, s85, v[156:157]
	v_add_u32_e32 v149, s16, v149
	v_cndmask_b32_e64 v83, v80, v152, s[0:1]
	v_mad_u64_u32 v[152:153], s[0:1], v149, s85, v[156:157]
	s_add_i32 s0, s69, 1
	s_and_b32 s0, s0, 7
	v_cmp_gt_u32_e32 vcc, s61, v149
	s_mulk_i32 s0, 0x1100
	v_add_u32_e32 v149, s0, v243
	v_cndmask_b32_e32 v80, v80, v152, vcc
	s_waitcnt lgkmcnt(0)
	v_mfma_f32_16x16x32_bf16 v[92:95], v[72:75], v[144:147], v[92:95]
	v_mfma_f32_16x16x32_bf16 v[96:99], v[64:67], v[144:147], v[96:99]
	v_mfma_f32_16x16x32_bf16 v[84:87], v[88:91], v[144:147], v[84:87]
	v_mfma_f32_16x16x32_bf16 v[68:71], v[76:79], v[144:147], v[68:71]
	ds_read_b128 v[144:147], v83
	v_mfma_f32_16x16x32_bf16 v[112:115], v[72:75], v[128:131], v[112:115]
	v_mfma_f32_16x16x32_bf16 v[108:111], v[64:67], v[128:131], v[108:111]
	v_mfma_f32_16x16x32_bf16 v[104:107], v[88:91], v[128:131], v[104:107]
	v_mfma_f32_16x16x32_bf16 v[100:103], v[76:79], v[128:131], v[100:103]
	ds_read_b128 v[128:131], v80
	ds_read_b128 v[76:79], v149 offset:160
	ds_read_b128 v[88:91], v149 offset:192
	v_mfma_f32_16x16x32_bf16 v[92:95], v[56:59], v[140:143], v[92:95]
	v_mfma_f32_16x16x32_bf16 v[96:99], v[60:63], v[140:143], v[96:99]
	v_mfma_f32_16x16x32_bf16 v[84:87], v[72:75], v[140:143], v[84:87]
	v_mfma_f32_16x16x32_bf16 v[68:71], v[64:67], v[140:143], v[68:71]
	ds_read_b128 v[140:143], v83 offset:64
	v_mfma_f32_16x16x32_bf16 v[112:115], v[56:59], v[124:127], v[112:115]
	v_mfma_f32_16x16x32_bf16 v[108:111], v[60:63], v[124:127], v[108:111]
	v_mfma_f32_16x16x32_bf16 v[104:107], v[72:75], v[124:127], v[104:107]
	v_mfma_f32_16x16x32_bf16 v[100:103], v[64:67], v[124:127], v[100:103]
	ds_read_b128 v[124:127], v80 offset:64
	ds_read_b128 v[64:67], v149 offset:224
	ds_read_b128 v[72:75], v149 offset:256
	v_mfma_f32_16x16x32_bf16 v[92:95], v[28:31], v[136:139], v[92:95]
	v_mfma_f32_16x16x32_bf16 v[96:99], v[24:27], v[136:139], v[96:99]
	v_mfma_f32_16x16x32_bf16 v[84:87], v[56:59], v[136:139], v[84:87]
	v_mfma_f32_16x16x32_bf16 v[68:71], v[60:63], v[136:139], v[68:71]
	ds_read_b128 v[136:139], v83 offset:128
	v_mfma_f32_16x16x32_bf16 v[112:115], v[28:31], v[120:123], v[112:115]
	v_mfma_f32_16x16x32_bf16 v[108:111], v[24:27], v[120:123], v[108:111]
	v_mfma_f32_16x16x32_bf16 v[104:107], v[56:59], v[120:123], v[104:107]
	v_mfma_f32_16x16x32_bf16 v[100:103], v[60:63], v[120:123], v[100:103]
	ds_read_b128 v[120:123], v80 offset:128
	ds_read_b128 v[60:63], v149 offset:288
	ds_read_b128 v[56:59], v149 offset:320
	v_mfma_f32_16x16x32_bf16 v[92:95], v[32:35], v[132:135], v[92:95]
	v_mfma_f32_16x16x32_bf16 v[96:99], v[36:39], v[132:135], v[96:99]
	v_mfma_f32_16x16x32_bf16 v[84:87], v[28:31], v[132:135], v[84:87]
	v_mfma_f32_16x16x32_bf16 v[68:71], v[24:27], v[132:135], v[68:71]
	ds_read_b128 v[132:135], v83 offset:192
	v_mfma_f32_16x16x32_bf16 v[112:115], v[32:35], v[116:119], v[112:115]
	v_mfma_f32_16x16x32_bf16 v[108:111], v[36:39], v[116:119], v[108:111]
	v_mfma_f32_16x16x32_bf16 v[104:107], v[28:31], v[116:119], v[104:107]
	v_mfma_f32_16x16x32_bf16 v[100:103], v[24:27], v[116:119], v[100:103]
	ds_read_b128 v[116:119], v80 offset:192
	ds_read_b128 v[24:27], v149 offset:352
	ds_read_b128 v[28:31], v149 offset:384
	ds_read_b128 v[36:39], v149 offset:416
	ds_read_b128 v[32:35], v149 offset:448
	s_setprio 0
	s_add_i32 s0, s69, 4
	s_cmp_ge_i32 s0, s87
	s_cbranch_scc1 .LBB0_424
	s_and_b32 s0, s0, 4
	s_and_b32 s1, s69, 3
	s_or_b32 s0, s0, s1
	s_mulk_i32 s0, 0x1100
	v_add_u32_e32 v80, s0, v157
	s_waitcnt vmcnt(0)
	ds_write2_b32 v80, v230, v231 offset1:32
	ds_write2_b32 v80, v238, v239 offset0:64 offset1:96

; #define LAS __attribute__((address_space(3)))
; #define CONV_HEAD() const int step = d - dmin; if (step + CONV_GRP < nsteps) CONV_LOADWIN(d + CONV_GRP); __builtin_amdgcn_sched_barrier(0)
; #define CONV_TAIL() if (step + CONV_GRP < nsteps) CONV_STOREWIN(step + CONV_GRP); if ((step & 1) == 1 || step + 1 == nsteps) __syncthreads()
; #define CONV_DS(x) ({ int t_ = (x); LAUNDER_S(t_); t_; })
; #define CONV_NB1(H) ((d + 1 <= hi0) ? CONV_BPH(0, H, d + 1) : CONV_BPH(1, H, d + 1))
; __device__ __forceinline__ void conv_item(const Params& P, int slice, int item, LAS unsigned char* lds) {
;     ...
;     for (int d = dmin; d < lo0; ++d) { CONV_HEAD(); CONV_TAIL(); }
;     {
;       const LAS unsigned char* wb = CONV_WB(lo0 - dmin); const LAS unsigned char* bp0 = CONV_BPH(0, 0, lo0); const LAS unsigned char* bp1 = CONV_BPH(0, 1, lo0);
; #pragma unroll
;       for (int k = 0; k < 10; ++k) fa[k] = *(const LAS bf16x8*)(wb + 32 * (k - 3));
; #pragma unroll
;       for (int ks = 0; ks < 4; ++ks) { fb[ks] = *(const LAS bf16x8*)(bp0 + 64 * ks); fb[4 + ks] = *(const LAS bf16x8*)(bp1 + 64 * ks); }
;     }
;     const int hw = 16 >> nbsh;
;     ...
;     for (int d = CONV_DS(lo0); d < lo0 + hw; ++d) { CONV_HEADT(); CONV_TILESTEP(0, CONV_BPH(0, 0, d + 1), CONV_BPH(0, 1, d + 1), 1, CONV_WB(step + 1), 1, 1); CONV_TAIL(); }
;     for (int d = CONV_DS(lo0 + hw); d < lo1; ++d) { CONV_HEADT(); CONV_TILESTEP(0, CONV_BPH(0, 0, d + 1), CONV_BPH(0, 1, d + 1), 1, CONV_WB(step + 1), 3, 1); CONV_TAIL(); }
;     for (int d = CONV_DS(lo1); d < lo1 + hw; ++d) { CONV_HEADT(); CONV_TILESTEP(0, CONV_BPH(1, 0, d), CONV_BPH(1, 1, d), 0, Wn, 3, 1);
;       CONV_TILESTEP(1, CONV_NB1(0), CONV_NB1(1), 1, CONV_WB(step + 1), 1, 0); CONV_TAIL(); }
;     for (int d = CONV_DS(lo1 + hw); d <= hi0 - hw; ++d) { CONV_HEADT(); CONV_TILESTEP(0, CONV_BPH(1, 0, d), CONV_BPH(1, 1, d), 0, Wn, 3, 1);
;       CONV_TILESTEP(1, CONV_NB1(0), CONV_NB1(1), 1, CONV_WB(step + 1), 3, 0); CONV_TAIL(); }
;     for (int d = CONV_DS(hi0 - hw + 1); d <= hi0; ++d) { CONV_HEADT(); CONV_TILESTEP(0, CONV_BPH(1, 0, d), CONV_BPH(1, 1, d), 0, Wn, 2, 1);
;       CONV_TILESTEP(1, CONV_NB1(0), CONV_NB1(1), 1, CONV_WB(step + 1), 3, 0); CONV_TAIL(); }
.LBB0_432:
	s_setprio 1
	v_lshl_add_u32 v240, v233, 1, v227
	global_load_dword v230, v240, s[8:9] offset:-2048
	global_load_dword v231, v240, s[8:9] offset:-1920
	global_load_dword v238, v240, s[8:9] offset:-1792
	global_load_dword v239, v240, s[8:9] offset:-1664
	v_add3_u32 v1, v247, s69, 1
	v_add3_u32 v6, v248, s69, 1
	s_add_i32 s71, s61, s68
	s_add_i32 s70, s71, -1
	s_waitcnt lgkmcnt(0)
	v_mfma_f32_16x16x32_bf16 v[2:5], v[72:75], v[128:131], v[52:55]
	v_mfma_f32_16x16x32_bf16 v[48:51], v[64:67], v[128:131], v[48:51]
	v_mfma_f32_16x16x32_bf16 v[44:47], v[88:91], v[128:131], v[44:47]
	v_mfma_f32_16x16x32_bf16 v[40:43], v[76:79], v[128:131], v[40:43]
	v_mov_b32_e32 v83, s29
	v_cmp_gt_u32_e32 vcc, s61, v1
	s_nop 1
	v_cndmask_b32_e32 v130, v83, v216, vcc
	v_cmp_gt_u32_e32 vcc, s61, v6
	s_nop 1
	v_cndmask_b32_e32 v138, v83, v82, vcc
	v_mfma_f32_16x16x32_bf16 v[2:5], v[56:59], v[124:127], v[2:5]
	v_mfma_f32_16x16x32_bf16 v[48:51], v[60:63], v[124:127], v[48:51]
	v_mfma_f32_16x16x32_bf16 v[44:47], v[72:75], v[124:127], v[44:47]
	v_mfma_f32_16x16x32_bf16 v[40:43], v[64:67], v[124:127], v[40:43]
	v_mfma_f32_16x16x32_bf16 v[48:51], v[24:27], v[120:123], v[48:51]
	v_mfma_f32_16x16x32_bf16 v[44:47], v[56:59], v[120:123], v[44:47]
	v_mfma_f32_16x16x32_bf16 v[40:43], v[60:63], v[120:123], v[40:43]
	v_mfma_f32_16x16x32_bf16 v[48:51], v[36:39], v[116:119], v[48:51]
	ds_read_b128 v[148:151], v138 offset:192
	v_mfma_f32_16x16x32_bf16 v[4:7], v[28:31], v[120:123], v[2:5]
	v_mfma_f32_16x16x32_bf16 v[44:47], v[28:31], v[116:119], v[44:47]
	v_mfma_f32_16x16x32_bf16 v[40:43], v[24:27], v[116:119], v[40:43]
	s_nop 0
	v_mfma_f32_16x16x32_bf16 v[52:55], v[32:35], v[116:119], v[4:7]
	ds_read_b128 v[116:119], v138 offset:128
	ds_read_b128 v[124:127], v138 offset:64
	ds_read_b128 v[136:139], v138
	ds_read_b128 v[132:135], v130 offset:64
	ds_read_b128 v[152:155], v130 offset:192
	ds_read_b128 v[120:123], v130 offset:128
	ds_read_b128 v[128:131], v130
	s_setprio 0
	s_setprio 1
	s_cmp_ge_i32 s68, s26
	s_cselect_b64 s[16:17], -1, 0
	s_cmp_lt_i32 s68, s26
	s_cselect_b64 vcc, -1, 0
	v_cndmask_b32_e32 v80, v247, v242, vcc
	v_add_u32_e32 v80, s69, v80
	v_cmp_gt_u32_e64 s[0:1], s61, v80
	v_mad_u64_u32 v[140:141], s[72:73], v80, s85, v[156:157]
	s_nop 0
	v_cndmask_b32_e64 v80, v83, v140, s[0:1]
	v_cndmask_b32_e32 v140, v248, v245, vcc
	v_add_u32_e32 v140, s69, v140
	v_cmp_gt_u32_e32 vcc, s61, v140
	v_mad_u64_u32 v[140:141], s[0:1], v140, s85, v[156:157]
	s_and_b32 s0, s71, 7
	s_mulk_i32 s0, 0x1100
	v_cndmask_b32_e32 v83, v83, v140, vcc
	v_add_u32_e32 v217, s0, v243
	s_waitcnt lgkmcnt(0)
	v_mfma_f32_16x16x32_bf16 v[92:95], v[72:75], v[128:131], v[92:95]
	v_mfma_f32_16x16x32_bf16 v[96:99], v[64:67], v[128:131], v[96:99]
	v_mfma_f32_16x16x32_bf16 v[84:87], v[88:91], v[128:131], v[84:87]
	v_mfma_f32_16x16x32_bf16 v[68:71], v[76:79], v[128:131], v[68:71]
	ds_read_b128 v[144:147], v80
	v_mfma_f32_16x16x32_bf16 v[112:115], v[72:75], v[136:139], v[112:115]
	v_mfma_f32_16x16x32_bf16 v[108:111], v[64:67], v[136:139], v[108:111]
	v_mfma_f32_16x16x32_bf16 v[104:107], v[88:91], v[136:139], v[104:107]
	v_mfma_f32_16x16x32_bf16 v[100:103], v[76:79], v[136:139], v[100:103]
	ds_read_b128 v[128:131], v83
	ds_read_b128 v[76:79], v217 offset:160
	ds_read_b128 v[88:91], v217 offset:192
	v_mfma_f32_16x16x32_bf16 v[92:95], v[56:59], v[132:135], v[92:95]
	v_mfma_f32_16x16x32_bf16 v[96:99], v[60:63], v[132:135], v[96:99]
	v_mfma_f32_16x16x32_bf16 v[84:87], v[72:75], v[132:135], v[84:87]
	v_mfma_f32_16x16x32_bf16 v[68:71], v[64:67], v[132:135], v[68:71]
	ds_read_b128 v[140:143], v80 offset:64
	v_mfma_f32_16x16x32_bf16 v[112:115], v[56:59], v[124:127], v[112:115]
	v_mfma_f32_16x16x32_bf16 v[108:111], v[60:63], v[124:127], v[108:111]
	v_mfma_f32_16x16x32_bf16 v[104:107], v[72:75], v[124:127], v[104:107]
	v_mfma_f32_16x16x32_bf16 v[100:103], v[64:67], v[124:127], v[100:103]
	ds_read_b128 v[124:127], v83 offset:64
	ds_read_b128 v[64:67], v217 offset:224
	ds_read_b128 v[72:75], v217 offset:256
	v_mfma_f32_16x16x32_bf16 v[92:95], v[28:31], v[120:123], v[92:95]
	v_mfma_f32_16x16x32_bf16 v[96:99], v[24:27], v[120:123], v[96:99]
	v_mfma_f32_16x16x32_bf16 v[84:87], v[56:59], v[120:123], v[84:87]
	v_mfma_f32_16x16x32_bf16 v[68:71], v[60:63], v[120:123], v[68:71]
	ds_read_b128 v[136:139], v80 offset:128
	v_mfma_f32_16x16x32_bf16 v[112:115], v[28:31], v[116:119], v[112:115]
	v_mfma_f32_16x16x32_bf16 v[108:111], v[24:27], v[116:119], v[108:111]
	v_mfma_f32_16x16x32_bf16 v[104:107], v[56:59], v[116:119], v[104:107]
	v_mfma_f32_16x16x32_bf16 v[100:103], v[60:63], v[116:119], v[100:103]
	ds_read_b128 v[120:123], v83 offset:128
	ds_read_b128 v[60:63], v217 offset:288
	ds_read_b128 v[56:59], v217 offset:320
	v_mfma_f32_16x16x32_bf16 v[92:95], v[32:35], v[152:155], v[92:95]
	v_mfma_f32_16x16x32_bf16 v[96:99], v[36:39], v[152:155], v[96:99]
	v_mfma_f32_16x16x32_bf16 v[84:87], v[28:31], v[152:155], v[84:87]
	v_mfma_f32_16x16x32_bf16 v[68:71], v[24:27], v[152:155], v[68:71]
	ds_read_b128 v[132:135], v80 offset:192
	v_mfma_f32_16x16x32_bf16 v[112:115], v[32:35], v[148:151], v[112:115]
	v_mfma_f32_16x16x32_bf16 v[108:111], v[36:39], v[148:151], v[108:111]
	v_mfma_f32_16x16x32_bf16 v[104:107], v[28:31], v[148:151], v[104:107]
	v_mfma_f32_16x16x32_bf16 v[100:103], v[24:27], v[148:151], v[100:103]
	ds_read_b128 v[116:119], v83 offset:192
	ds_read_b128 v[24:27], v217 offset:352
	ds_read_b128 v[28:31], v217 offset:384
	ds_read_b128 v[36:39], v217 offset:416
	ds_read_b128 v[32:35], v217 offset:448
	s_setprio 0
	s_add_i32 s0, s71, 3
	s_cmp_ge_i32 s0, s87
	s_cbranch_scc1 .LBB0_434
	s_and_b32 s0, s0, 4
	s_and_b32 s1, s70, 3
	s_or_b32 s0, s0, s1
	s_mulk_i32 s0, 0x1100
	v_add_u32_e32 v80, s0, v157
	s_waitcnt vmcnt(0)
	ds_write2_b32 v80, v230, v231 offset1:32
	ds_write2_b32 v80, v238, v239 offset0:64 offset1:96

; #define LAS __attribute__((address_space(3)))
; #define CONV_HEAD() const int step = d - dmin; if (step + CONV_GRP < nsteps) CONV_LOADWIN(d + CONV_GRP); __builtin_amdgcn_sched_barrier(0)
; #define CONV_TAIL() if (step + CONV_GRP < nsteps) CONV_STOREWIN(step + CONV_GRP); if ((step & 1) == 1 || step + 1 == nsteps) __syncthreads()
; #define CONV_DS(x) ({ int t_ = (x); LAUNDER_S(t_); t_; })
; #define CONV_NB1(H) ((d + 1 <= hi0) ? CONV_BPH(0, H, d + 1) : CONV_BPH(1, H, d + 1))
; __device__ __forceinline__ void conv_item(const Params& P, int slice, int item, LAS unsigned char* lds) {
;     ...
;     for (int d = dmin; d < lo0; ++d) { CONV_HEAD(); CONV_TAIL(); }
;     {
;       const LAS unsigned char* wb = CONV_WB(lo0 - dmin); const LAS unsigned char* bp0 = CONV_BPH(0, 0, lo0); const LAS unsigned char* bp1 = CONV_BPH(0, 1, lo0);
; #pragma unroll
;       for (int k = 0; k < 10; ++k) fa[k] = *(const LAS bf16x8*)(wb + 32 * (k - 3));
; #pragma unroll
;       for (int ks = 0; ks < 4; ++ks) { fb[ks] = *(const LAS bf16x8*)(bp0 + 64 * ks); fb[4 + ks] = *(const LAS bf16x8*)(bp1 + 64 * ks); }
;     }
;     const int hw = 16 >> nbsh;
;     ...
;     for (int d = CONV_DS(lo0); d < lo0 + hw; ++d) { CONV_HEADT(); CONV_TILESTEP(0, CONV_BPH(0, 0, d + 1), CONV_BPH(0, 1, d + 1), 1, CONV_WB(step + 1), 1, 1); CONV_TAIL(); }
;     for (int d = CONV_DS(lo0 + hw); d < lo1; ++d) { CONV_HEADT(); CONV_TILESTEP(0, CONV_BPH(0, 0, d + 1), CONV_BPH(0, 1, d + 1), 1, CONV_WB(step + 1), 3, 1); CONV_TAIL(); }
;     for (int d = CONV_DS(lo1); d < lo1 + hw; ++d) { CONV_HEADT(); CONV_TILESTEP(0, CONV_BPH(1, 0, d), CONV_BPH(1, 1, d), 0, Wn, 3, 1);
;       CONV_TILESTEP(1, CONV_NB1(0), CONV_NB1(1), 1, CONV_WB(step + 1), 1, 0); CONV_TAIL(); }
;     for (int d = CONV_DS(lo1 + hw); d <= hi0 - hw; ++d) { CONV_HEADT(); CONV_TILESTEP(0, CONV_BPH(1, 0, d), CONV_BPH(1, 1, d), 0, Wn, 3, 1);
;       CONV_TILESTEP(1, CONV_NB1(0), CONV_NB1(1), 1, CONV_WB(step + 1), 3, 0); CONV_TAIL(); }
;     for (int d = CONV_DS(hi0 - hw + 1); d <= hi0; ++d) { CONV_HEADT(); CONV_TILESTEP(0, CONV_BPH(1, 0, d), CONV_BPH(1, 1, d), 0, Wn, 2, 1);
;       CONV_TILESTEP(1, CONV_NB1(0), CONV_NB1(1), 1, CONV_WB(step + 1), 3, 0); CONV_TAIL(); }
;     for (int d = CONV_DS(hi0 + 1); d <= hi1 - hw; ++d) { CONV_HEADT(); CONV_TILESTEP(1, CONV_BPH(1, 0, d + 1), CONV_BPH(1, 1, d + 1), 1, CONV_WB(step + 1), 3, 1); CONV_TAIL(); }
.LBB0_439:
	s_add_i32 s17, s61, s16
	s_setprio 1
	v_lshl_add_u32 v240, v82, 1, v227
	global_load_dword v230, v240, s[8:9] offset:-2048
	global_load_dword v231, v240, s[8:9] offset:-1920
	global_load_dword v238, v240, s[8:9] offset:-1792
	global_load_dword v239, v240, s[8:9] offset:-1664
	v_add_u32_e32 v154, s30, v83
	s_add_i32 s0, s17, 1
	s_and_b32 s0, s0, 7
	s_mulk_i32 s0, 0x1100
	s_waitcnt lgkmcnt(1)
	v_mfma_f32_16x16x32_bf16 v[0:3], v[72:75], v[144:147], v[92:95]
	v_mfma_f32_16x16x32_bf16 v[4:7], v[64:67], v[144:147], v[96:99]
	v_mfma_f32_16x16x32_bf16 v[84:87], v[88:91], v[144:147], v[84:87]
	v_mfma_f32_16x16x32_bf16 v[68:71], v[76:79], v[144:147], v[68:71]
	s_waitcnt lgkmcnt(0)
	v_mfma_f32_16x16x32_bf16 v[92:95], v[72:75], v[128:131], v[112:115]
	v_mfma_f32_16x16x32_bf16 v[0:3], v[56:59], v[140:143], v[0:3]
	v_mfma_f32_16x16x32_bf16 v[92:95], v[56:59], v[124:127], v[92:95]
	v_mfma_f32_16x16x32_bf16 v[0:3], v[28:31], v[136:139], v[0:3]
	v_mfma_f32_16x16x32_bf16 v[96:99], v[28:31], v[120:123], v[92:95]
	v_mfma_f32_16x16x32_bf16 v[92:95], v[32:35], v[132:135], v[0:3]
	v_mfma_f32_16x16x32_bf16 v[112:115], v[32:35], v[116:119], v[96:99]
	v_mfma_f32_16x16x32_bf16 v[96:99], v[64:67], v[128:131], v[108:111]
	s_nop 3
	v_mfma_f32_16x16x32_bf16 v[88:91], v[88:91], v[128:131], v[104:107]
	v_mfma_f32_16x16x32_bf16 v[84:87], v[72:75], v[140:143], v[84:87]
	v_mfma_f32_16x16x32_bf16 v[72:75], v[72:75], v[124:127], v[88:91]
	v_mfma_f32_16x16x32_bf16 v[76:79], v[76:79], v[128:131], v[100:103]
	v_mfma_f32_16x16x32_bf16 v[84:87], v[56:59], v[136:139], v[84:87]
	v_mfma_f32_16x16x32_bf16 v[56:59], v[56:59], v[120:123], v[72:75]
	v_mfma_f32_16x16x32_bf16 v[84:87], v[28:31], v[132:135], v[84:87]
	v_mfma_f32_16x16x32_bf16 v[104:107], v[28:31], v[116:119], v[56:59]
	s_nop 1
	s_nop 0
	v_mov_b32_e32 v72, s29
	v_mfma_f32_16x16x32_bf16 v[2:5], v[60:63], v[140:143], v[4:7]
	v_mfma_f32_16x16x32_bf16 v[56:59], v[60:63], v[124:127], v[96:99]
	v_mfma_f32_16x16x32_bf16 v[2:5], v[24:27], v[136:139], v[2:5]
	v_mfma_f32_16x16x32_bf16 v[56:59], v[24:27], v[120:123], v[56:59]
	v_mfma_f32_16x16x32_bf16 v[96:99], v[36:39], v[132:135], v[2:5]
	v_mfma_f32_16x16x32_bf16 v[2:5], v[64:67], v[140:143], v[68:71]
	v_mfma_f32_16x16x32_bf16 v[108:111], v[36:39], v[116:119], v[56:59]
	v_mfma_f32_16x16x32_bf16 v[56:59], v[64:67], v[124:127], v[76:79]
	v_mfma_f32_16x16x32_bf16 v[2:5], v[60:63], v[136:139], v[2:5]
	v_mfma_f32_16x16x32_bf16 v[68:71], v[24:27], v[132:135], v[2:5]
	s_nop 6
	v_mfma_f32_16x16x32_bf16 v[56:59], v[60:63], v[120:123], v[56:59]
	v_mfma_f32_16x16x32_bf16 v[100:103], v[24:27], v[116:119], v[56:59]
	s_nop 6
	v_cmp_gt_u32_e32 vcc, s61, v83
	s_nop 1
	v_cndmask_b32_e32 v136, v72, v149, vcc
	ds_read_b128 v[140:143], v136 offset:64
	ds_read_b128 v[144:147], v136
	ds_read_b128 v[132:135], v136 offset:192
	ds_read_b128 v[136:139], v136 offset:128
	v_add_u32_e32 v155, s0, v243
	v_cmp_gt_u32_e64 s[0:1], s61, v154
	s_nop 1
	v_cndmask_b32_e64 v74, v72, v148, s[0:1]
	ds_read_b128 v[88:91], v155 offset:192
	ds_read_b128 v[124:127], v74 offset:64
	ds_read_b128 v[120:123], v74 offset:128
	ds_read_b128 v[128:131], v74
	ds_read_b128 v[116:119], v74 offset:192
	ds_read_b128 v[72:75], v155 offset:256
	ds_read_b128 v[32:35], v155 offset:448
	ds_read_b128 v[76:79], v155 offset:160
	ds_read_b128 v[28:31], v155 offset:384
	ds_read_b128 v[64:67], v155 offset:224
	ds_read_b128 v[36:39], v155 offset:416
	ds_read_b128 v[24:27], v155 offset:352
	ds_read_b128 v[60:63], v155 offset:288
	ds_read_b128 v[56:59], v155 offset:320
	s_setprio 0
	s_add_i32 s0, s17, 4
	s_cmp_ge_i32 s0, s87
	s_cbranch_scc1 .LBB0_441
	s_and_b32 s0, s0, 4
	s_and_b32 s1, s17, 3
	s_or_b32 s0, s0, s1
	s_mulk_i32 s0, 0x1100
	v_add_u32_e32 v80, s0, v157
	s_waitcnt vmcnt(0)
	ds_write2_b32 v80, v230, v231 offset1:32
	ds_write2_b32 v80, v238, v239 offset0:64 offset1:96

; #define LAS __attribute__((address_space(3)))
; #define CONV_HEAD() const int step = d - dmin; if (step + CONV_GRP < nsteps) CONV_LOADWIN(d + CONV_GRP); __builtin_amdgcn_sched_barrier(0)
; #define CONV_TAIL() if (step + CONV_GRP < nsteps) CONV_STOREWIN(step + CONV_GRP); if ((step & 1) == 1 || step + 1 == nsteps) __syncthreads()
; __device__ __forceinline__ void conv_item(const Params& P, int slice, int item, LAS unsigned char* lds) {
;     ...
;     for (int d = dmin; d < lo0; ++d) { CONV_HEAD(); CONV_TAIL(); }
;     {
;       const LAS unsigned char* wb = CONV_WB(lo0 - dmin); const LAS unsigned char* bp0 = CONV_BPH(0, 0, lo0); const LAS unsigned char* bp1 = CONV_BPH(0, 1, lo0);
; #pragma unroll
;       for (int k = 0; k < 10; ++k) fa[k] = *(const LAS bf16x8*)(wb + 32 * (k - 3));
; #pragma unroll
;       for (int ks = 0; ks < 4; ++ks) { fb[ks] = *(const LAS bf16x8*)(bp0 + 64 * ks); fb[4 + ks] = *(const LAS bf16x8*)(bp1 + 64 * ks); }
;     }
;     const int hw = 16 >> nbsh;
;     ...
;     for (int d = CONV_DS(lo0); d < lo0 + hw; ++d) { CONV_HEADT(); CONV_TILESTEP(0, CONV_BPH(0, 0, d + 1), CONV_BPH(0, 1, d + 1), 1, CONV_WB(step + 1), 1, 1); CONV_TAIL(); }
;     for (int d = CONV_DS(lo0 + hw); d < lo1; ++d) { CONV_HEADT(); CONV_TILESTEP(0, CONV_BPH(0, 0, d + 1), CONV_BPH(0, 1, d + 1), 1, CONV_WB(step + 1), 3, 1); CONV_TAIL(); }
;     for (int d = CONV_DS(lo1); d < lo1 + hw; ++d) { CONV_HEADT(); CONV_TILESTEP(0, CONV_BPH(1, 0, d), CONV_BPH(1, 1, d), 0, Wn, 3, 1);
;       CONV_TILESTEP(1, CONV_NB1(0), CONV_NB1(1), 1, CONV_WB(step + 1), 1, 0); CONV_TAIL(); }
;     for (int d = CONV_DS(lo1 + hw); d <= hi0 - hw; ++d) { CONV_HEADT(); CONV_TILESTEP(0, CONV_BPH(1, 0, d), CONV_BPH(1, 1, d), 0, Wn, 3, 1);
;       CONV_TILESTEP(1, CONV_NB1(0), CONV_NB1(1), 1, CONV_WB(step + 1), 3, 0); CONV_TAIL(); }
;     for (int d = CONV_DS(hi0 - hw + 1); d <= hi0; ++d) { CONV_HEADT(); CONV_TILESTEP(0, CONV_BPH(1, 0, d), CONV_BPH(1, 1, d), 0, Wn, 2, 1);
;       CONV_TILESTEP(1, CONV_NB1(0), CONV_NB1(1), 1, CONV_WB(step + 1), 3, 0); CONV_TAIL(); }
;     for (int d = CONV_DS(hi0 + 1); d <= hi1 - hw; ++d) { CONV_HEADT(); CONV_TILESTEP(1, CONV_BPH(1, 0, d + 1), CONV_BPH(1, 1, d + 1), 1, CONV_WB(step + 1), 3, 1); CONV_TAIL(); }
;     for (int d = CONV_DS(hi1 - hw + 1); d <= hi1; ++d) { CONV_HEADT(); CONV_TILESTEP(1, CONV_BPH(1, 0, d + 1), CONV_BPH(1, 1, d + 1), 1, CONV_WB(step + 1), 2, 1); CONV_TAIL(); }
.LBB0_446:
	s_add_i32 s17, s61, s16
	s_setprio 1
	v_lshl_add_u32 v240, v82, 1, v227
	global_load_dword v230, v240, s[8:9] offset:-2048
	global_load_dword v231, v240, s[8:9] offset:-1920
	global_load_dword v238, v240, s[8:9] offset:-1792
	global_load_dword v239, v240, s[8:9] offset:-1664
	s_add_i32 s0, s17, 1
	s_and_b32 s0, s0, 7
	s_mulk_i32 s0, 0x1100
	s_waitcnt lgkmcnt(0)
	v_mfma_f32_16x16x32_bf16 v[2:5], v[72:75], v[128:131], v[112:115]
	v_mfma_f32_16x16x32_bf16 v[108:111], v[64:67], v[128:131], v[108:111]
	v_mfma_f32_16x16x32_bf16 v[88:91], v[88:91], v[128:131], v[104:107]
	v_mfma_f32_16x16x32_bf16 v[76:79], v[76:79], v[128:131], v[100:103]
	v_mfma_f32_16x16x32_bf16 v[2:5], v[56:59], v[124:127], v[2:5]
	v_mfma_f32_16x16x32_bf16 v[100:103], v[60:63], v[124:127], v[108:111]
	v_mfma_f32_16x16x32_bf16 v[72:75], v[72:75], v[124:127], v[88:91]
	v_mfma_f32_16x16x32_bf16 v[64:67], v[64:67], v[124:127], v[76:79]
	v_mfma_f32_16x16x32_bf16 v[4:7], v[28:31], v[120:123], v[2:5]
	v_mfma_f32_16x16x32_bf16 v[76:79], v[24:27], v[120:123], v[100:103]
	v_mfma_f32_16x16x32_bf16 v[60:63], v[60:63], v[120:123], v[64:67]
	v_add_u32_e32 v133, s0, v243
	v_mfma_f32_16x16x32_bf16 v[112:115], v[32:35], v[116:119], v[4:7]
	v_mfma_f32_16x16x32_bf16 v[100:103], v[24:27], v[116:119], v[60:63]
	v_cmp_gt_u32_e64 s[0:1], s61, v83
	s_nop 1
	v_mov_b32_e32 v5, s29
	s_nop 0
	s_nop 1
	v_cndmask_b32_e64 v62, v5, v132, s[0:1]
	v_mfma_f32_16x16x32_bf16 v[72:75], v[56:59], v[120:123], v[72:75]
	v_mfma_f32_16x16x32_bf16 v[108:111], v[36:39], v[116:119], v[76:79]
	v_mfma_f32_16x16x32_bf16 v[104:107], v[28:31], v[116:119], v[72:75]
	ds_read_b128 v[116:119], v62 offset:192
	ds_read_b128 v[128:131], v62
	ds_read_b128 v[124:127], v62 offset:64
	ds_read_b128 v[120:123], v62 offset:128
	ds_read_b128 v[60:63], v133 offset:288
	ds_read_b128 v[56:59], v133 offset:320
	ds_read_b128 v[32:35], v133 offset:448
	ds_read_b128 v[24:27], v133 offset:352
	ds_read_b128 v[28:31], v133 offset:384
	ds_read_b128 v[36:39], v133 offset:416
	ds_read_b128 v[76:79], v133 offset:160
	ds_read_b128 v[88:91], v133 offset:192
	ds_read_b128 v[64:67], v133 offset:224
	ds_read_b128 v[72:75], v133 offset:256
	s_setprio 0
	s_add_i32 s0, s17, 4
	s_cmp_ge_i32 s0, s87
	s_cbranch_scc1 .LBB0_448
	s_and_b32 s0, s0, 4
	s_and_b32 s1, s17, 3
	s_or_b32 s0, s0, s1
	s_mulk_i32 s0, 0x1100
	v_add_u32_e32 v80, s0, v157
	s_waitcnt vmcnt(0)
	ds_write2_b32 v80, v230, v231 offset1:32
	ds_write2_b32 v80, v238, v239 offset0:64 offset1:96

; #define LAS __attribute__((address_space(3)))
; #define LAUNDER_S(x) asm volatile("" : "+s"(x))
; #define CONV_DS(x) ({ int t_ = (x); LAUNDER_S(t_); t_; })
; __device__ __forceinline__ void conv_item(const Params& P, int slice, int item, LAS unsigned char* lds) {
;     ...
;     for (int d = dmin; d < lo0; ++d) { CONV_HEAD(); CONV_TAIL(); }
;     {
;       const LAS unsigned char* wb = CONV_WB(lo0 - dmin); const LAS unsigned char* bp0 = CONV_BPH(0, 0, lo0); const LAS unsigned char* bp1 = CONV_BPH(0, 1, lo0);
; #pragma unroll
;       for (int k = 0; k < 10; ++k) fa[k] = *(const LAS bf16x8*)(wb + 32 * (k - 3));
; #pragma unroll
;       for (int ks = 0; ks < 4; ++ks) { fb[ks] = *(const LAS bf16x8*)(bp0 + 64 * ks); fb[4 + ks] = *(const LAS bf16x8*)(bp1 + 64 * ks); }
;     }
;     const int hw = 16 >> nbsh;
;     ...
;     for (int d = CONV_DS(lo0); d < lo0 + hw; ++d) { CONV_HEADT(); CONV_TILESTEP(0, CONV_BPH(0, 0, d + 1), CONV_BPH(0, 1, d + 1), 1, CONV_WB(step + 1), 1, 1); CONV_TAIL(); }
;     for (int d = CONV_DS(lo0 + hw); d < lo1; ++d) { CONV_HEADT(); CONV_TILESTEP(0, CONV_BPH(0, 0, d + 1), CONV_BPH(0, 1, d + 1), 1, CONV_WB(step + 1), 3, 1); CONV_TAIL(); }
;     for (int d = CONV_DS(lo1); d < lo1 + hw; ++d) { CONV_HEADT(); CONV_TILESTEP(0, CONV_BPH(1, 0, d), CONV_BPH(1, 1, d), 0, Wn, 3, 1);
;       CONV_TILESTEP(1, CONV_NB1(0), CONV_NB1(1), 1, CONV_WB(step + 1), 1, 0); CONV_TAIL(); }
;     for (int d = CONV_DS(lo1 + hw); d <= hi0 - hw; ++d) { CONV_HEADT(); CONV_TILESTEP(0, CONV_BPH(1, 0, d), CONV_BPH(1, 1, d), 0, Wn, 3, 1);
;       CONV_TILESTEP(1, CONV_NB1(0), CONV_NB1(1), 1, CONV_WB(step + 1), 3, 0); CONV_TAIL(); }
;     for (int d = CONV_DS(hi0 - hw + 1); d <= hi0; ++d) { CONV_HEADT(); CONV_TILESTEP(0, CONV_BPH(1, 0, d), CONV_BPH(1, 1, d), 0, Wn, 2, 1);
;       CONV_TILESTEP(1, CONV_NB1(0), CONV_NB1(1), 1, CONV_WB(step + 1), 3, 0); CONV_TAIL(); }
;     for (int d = CONV_DS(hi0 + 1); d <= hi1 - hw; ++d) { CONV_HEADT(); CONV_TILESTEP(1, CONV_BPH(1, 0, d + 1), CONV_BPH(1, 1, d + 1), 1, CONV_WB(step + 1), 3, 1); CONV_TAIL(); }
;     for (int d = CONV_DS(hi1 - hw + 1); d <= hi1; ++d) { CONV_HEADT(); CONV_TILESTEP(1, CONV_BPH(1, 0, d + 1), CONV_BPH(1, 1, d + 1), 1, CONV_WB(step + 1), 2, 1); CONV_TAIL(); }
;     ...
;     { int dl_ = hi1 + 1; LAUNDER_S(dl_); for (int d = dl_; d < nblk; ++d) { CONV_HEAD(); CONV_TAIL(); } }
.LBB0_453:
	s_add_i32 s68, s61, s16
	s_add_i32 s17, s68, 3
	s_cmp_lt_i32 s17, s87
	s_cselect_b64 s[0:1], -1, 0
	s_cmp_ge_i32 s17, s87
	s_cbranch_scc1 .LBB0_455
	v_lshl_add_u32 v240, v24, 1, v227
	global_load_dword v230, v240, s[8:9] offset:-2048
	global_load_dword v231, v240, s[8:9] offset:-1920
	global_load_dword v238, v240, s[8:9] offset:-1792
	global_load_dword v239, v240, s[8:9] offset:-1664
.LBB0_455:
	s_add_i32 s68, s68, -1
	s_andn2_b64 vcc, exec, s[0:1]
	s_cbranch_vccnz .LBB0_457
	s_and_b32 s0, s17, 4
	s_and_b32 s1, s68, 3
	s_or_b32 s0, s0, s1
	s_mulk_i32 s0, 0x1100
	v_add_u32_e32 v25, s0, v157
	s_waitcnt vmcnt(0)
	ds_write2_b32 v25, v230, v231 offset1:32
	ds_write2_b32 v25, v238, v239 offset0:64 offset1:96
